# v17_ilv
# baseline (speedup 1.0000x reference)
; #define MFMA32(a, b, c) __builtin_amdgcn_mfma_f32_32x32x16_bf16((a), (b), (c), 0, 0, 0)
; template <int DQK, int MODE>
; DI void attn_core(const u16* __restrict__ Qg, int ldq, const u16* __restrict__ Kg, int ldk, const u16* __restrict__ Vtg,
;                   const u64* __restrict__ maskg, int q0, float scale, char* smem, int* sflags, f32x16 (&o)[4], float& l_run) {
;     ...
;       for (int kt = 0; kt < 2; ++kt)
; #pragma unroll
;         for (int i = 0; i < 16; ++i) {
;           float pv = __builtin_amdgcn_exp2f(__builtin_fmaf(s[kt][i], sc, msc));
;           if (MODE == 1) pv = (s[kt][i] > -1e29f) ? pv : 0.f;
;           s[kt][i] = pv;
;           ls += pv;
;         }
;     ...
; #pragma unroll
;     for (int kt = 0; kt < 2; ++kt)
; #pragma unroll
;       for (int sb = 0; sb < 2; ++sb) {
;         const bf16x8 pf = pack8(s[kt][8 * sb + 0], s[kt][8 * sb + 1], s[kt][8 * sb + 2], s[kt][8 * sb + 3],
;                                 s[kt][8 * sb + 4], s[kt][8 * sb + 5], s[kt][8 * sb + 6], s[kt][8 * sb + 7]);
; #pragma unroll
;         for (int t = 0; t < 4; ++t) {
;           const bf16x8 vf = *(const bf16x8*)(Vs + (32 * t + l31) * 72 + 32 * kt + 16 * sb + hh * 8);
;           o[t] = MFMA32(vf, pf, o[t]);
;         }
;       }
.LBB0_154:
	v_mul_f32_e32 v106, 0xbe0293ee, v2
	v_fmamk_f32 v0, v200, 0x3e0293ee, v106
	v_exp_f32_e32 v0, v0
	v_fmamk_f32 v82, v187, 0x3e0293ee, v106
	v_exp_f32_e32 v82, v82
	v_cmp_lt_f32_e32 vcc, s18, v200
	v_fmamk_f32 v84, v105, 0x3e0293ee, v106
	v_exp_f32_e32 v84, v84
	v_cndmask_b32_e32 v83, 0, v0, vcc
	v_cmp_lt_f32_e32 vcc, s18, v187
	v_fmamk_f32 v85, v104, 0x3e0293ee, v106
	v_exp_f32_e32 v85, v85
	v_cndmask_b32_e32 v86, 0, v82, vcc
	v_fmamk_f32 v82, v199, 0x3e0293ee, v106
	v_exp_f32_e32 v82, v82
	v_cmp_lt_f32_e32 vcc, s18, v199
	v_fmamk_f32 v88, v103, 0x3e0293ee, v106
	v_exp_f32_e32 v88, v88
	v_cndmask_b32_e32 v87, 0, v82, vcc
	v_fmamk_f32 v82, v198, 0x3e0293ee, v106
	v_exp_f32_e32 v82, v82
	v_cmp_lt_f32_e32 vcc, s18, v198
	v_fmamk_f32 v89, v102, 0x3e0293ee, v106
	v_exp_f32_e32 v89, v89
	v_cndmask_b32_e32 v90, 0, v82, vcc
	v_fmamk_f32 v82, v201, 0x3e0293ee, v106
	v_exp_f32_e32 v82, v82
	v_cmp_lt_f32_e32 vcc, s18, v201
	v_fmamk_f32 v92, v10, 0x3e0293ee, v106
	v_exp_f32_e32 v92, v92
	v_cndmask_b32_e32 v91, 0, v82, vcc
	v_fmamk_f32 v82, v96, 0x3e0293ee, v106
	v_exp_f32_e32 v82, v82
	v_cmp_lt_f32_e32 vcc, s18, v96
	v_add_f32_e32 v0, 0, v83
	v_add_f32_e32 v0, v86, v0
	v_cndmask_b32_e32 v95, 0, v82, vcc
	v_fmamk_f32 v82, v186, 0x3e0293ee, v106
	v_exp_f32_e32 v82, v82
	v_cmp_lt_f32_e32 vcc, s18, v186
	v_add_f32_e32 v0, v87, v0
	v_add_f32_e32 v0, v90, v0
	v_cndmask_b32_e32 v96, 0, v82, vcc
	v_fmamk_f32 v82, v97, 0x3e0293ee, v106
	v_exp_f32_e32 v82, v82
	v_cmp_lt_f32_e32 vcc, s18, v97
	v_add_f32_e32 v0, v91, v0
	v_add_f32_e32 v0, v95, v0
	v_cndmask_b32_e32 v97, 0, v82, vcc
	s_nop 0
	v_cvt_pk_bf16_f32 v242, v83, v86
	v_cvt_pk_bf16_f32 v243, v87, v90
	v_cvt_pk_bf16_f32 v244, v91, v95
	v_cvt_pk_bf16_f32 v245, v96, v97
	s_nop 1
	v_add_u32_e32 v83, v174, v175
	ds_read_b128 v[198:201], v83 offset:17408
	ds_read_b128 v[202:205], v83 offset:22016
	ds_read_b128 v[210:213], v83 offset:26624
	ds_read_b128 v[214:217], v83 offset:31232
	ds_read_b128 v[218:221], v83 offset:17440
	ds_read_b128 v[226:229], v83 offset:22048
	s_waitcnt lgkmcnt(5)
	v_mfma_f32_32x32x16_bf16 v[64:79], v[198:201], v[242:245], v[64:79]
	ds_read_b128 v[198:201], v83 offset:26656
	v_fmamk_f32 v82, v185, 0x3e0293ee, v106
	v_exp_f32_e32 v82, v82
	v_cmp_lt_f32_e32 vcc, s18, v185
	v_add_f32_e32 v0, v96, v0
	v_add_f32_e32 v0, v97, v0
	v_cndmask_b32_e32 v82, 0, v82, vcc
	v_cmp_lt_f32_e32 vcc, s18, v105
	v_add_f32_e32 v0, v82, v0
	v_mov_b32_e32 v184, v2
	s_waitcnt lgkmcnt(5)
	v_mfma_f32_32x32x16_bf16 v[48:63], v[202:205], v[242:245], v[48:63]
	ds_read_b128 v[202:205], v83 offset:31264
	v_cndmask_b32_e32 v84, 0, v84, vcc
	v_cmp_lt_f32_e32 vcc, s18, v104
	v_add_f32_e32 v0, v84, v0
	s_nop 0
	v_cndmask_b32_e32 v85, 0, v85, vcc
	v_cmp_lt_f32_e32 vcc, s18, v103
	v_add_f32_e32 v0, v85, v0
	s_nop 0
	v_cndmask_b32_e32 v88, 0, v88, vcc
	s_waitcnt lgkmcnt(5)
	v_mfma_f32_32x32x16_bf16 v[32:47], v[210:213], v[242:245], v[32:47]
	ds_read_b128 v[210:213], v83 offset:17472
	v_cmp_lt_f32_e32 vcc, s18, v102
	v_add_f32_e32 v0, v88, v0
	s_nop 0
	v_cndmask_b32_e32 v89, 0, v89, vcc
	v_cmp_lt_f32_e32 vcc, s18, v10
	v_fmamk_f32 v10, v100, 0x3e0293ee, v106
	v_exp_f32_e32 v10, v10
	v_cndmask_b32_e32 v92, 0, v92, vcc
	v_cmp_lt_f32_e32 vcc, s18, v100
	s_waitcnt lgkmcnt(5)
	v_mfma_f32_32x32x16_bf16 v[16:31], v[214:217], v[242:245], v[16:31]
	ds_read_b128 v[214:217], v83 offset:22080
	v_add_f32_e32 v0, v89, v0
	v_add_f32_e32 v0, v92, v0
	v_cndmask_b32_e32 v93, 0, v10, vcc
	v_fmamk_f32 v10, v11, 0x3e0293ee, v106
	v_exp_f32_e32 v10, v10
	v_cmp_lt_f32_e32 vcc, s18, v11
	v_fmamk_f32 v11, v99, 0x3e0293ee, v106
	v_exp_f32_e32 v11, v11
	v_cndmask_b32_e32 v94, 0, v10, vcc
	s_nop 0
	v_cvt_pk_bf16_f32 v242, v82, v84
	v_cvt_pk_bf16_f32 v243, v85, v88
	v_cvt_pk_bf16_f32 v244, v89, v92
	v_cvt_pk_bf16_f32 v245, v93, v94
	s_nop 1
	s_waitcnt lgkmcnt(5)
; #define MFMA32(a, b, c) __builtin_amdgcn_mfma_f32_32x32x16_bf16((a), (b), (c), 0, 0, 0)
; template <int DQK, int MODE>
; DI void attn_core(const u16* __restrict__ Qg, int ldq, const u16* __restrict__ Kg, int ldk, const u16* __restrict__ Vtg,
;                   const u64* __restrict__ maskg, int q0, float scale, char* smem, int* sflags, f32x16 (&o)[4], float& l_run) {
;     ...
;       for (int kt = 0; kt < 2; ++kt)
; #pragma unroll
;         for (int i = 0; i < 16; ++i) {
;           float pv = __builtin_amdgcn_exp2f(__builtin_fmaf(s[kt][i], sc, msc));
;           if (MODE == 1) pv = (s[kt][i] > -1e29f) ? pv : 0.f;
;           s[kt][i] = pv;
;           ls += pv;
;         }
;     ...
; #pragma unroll
;     for (int kt = 0; kt < 2; ++kt)
; #pragma unroll
;       for (int sb = 0; sb < 2; ++sb) {
;         const bf16x8 pf = pack8(s[kt][8 * sb + 0], s[kt][8 * sb + 1], s[kt][8 * sb + 2], s[kt][8 * sb + 3],
;                                 s[kt][8 * sb + 4], s[kt][8 * sb + 5], s[kt][8 * sb + 6], s[kt][8 * sb + 7]);
; #pragma unroll
;         for (int t = 0; t < 4; ++t) {
;           const bf16x8 vf = *(const bf16x8*)(Vs + (32 * t + l31) * 72 + 32 * kt + 16 * sb + hh * 8);
;           o[t] = MFMA32(vf, pf, o[t]);
;         }
;       }
	v_mfma_f32_32x32x16_bf16 v[64:79], v[218:221], v[242:245], v[64:79]
	ds_read_b128 v[218:221], v83 offset:26688
	v_fmamk_f32 v10, v101, 0x3e0293ee, v106
	v_exp_f32_e32 v10, v10
	v_cmp_lt_f32_e32 vcc, s18, v101
	v_add_f32_e32 v0, v93, v0
	v_add_f32_e32 v0, v94, v0
	v_cndmask_b32_e32 v10, 0, v10, vcc
	v_cmp_lt_f32_e32 vcc, s18, v99
	v_fmamk_f32 v99, v12, 0x3e0293ee, v106
	v_exp_f32_e32 v99, v99
	v_cndmask_b32_e32 v11, 0, v11, vcc
	v_cmp_lt_f32_e32 vcc, s18, v12
	s_waitcnt lgkmcnt(5)
	v_mfma_f32_32x32x16_bf16 v[48:63], v[226:229], v[242:245], v[48:63]
	ds_read_b128 v[226:229], v83 offset:31296
	v_add_f32_e32 v0, v10, v0
	v_add_f32_e32 v0, v11, v0
	v_cndmask_b32_e32 v12, 0, v99, vcc
	v_fmamk_f32 v99, v13, 0x3e0293ee, v106
	v_exp_f32_e32 v99, v99
	v_cmp_lt_f32_e32 vcc, s18, v13
	v_add_f32_e32 v0, v12, v0
	s_nop 0
	v_cndmask_b32_e32 v13, 0, v99, vcc
	v_fmamk_f32 v99, v14, 0x3e0293ee, v106
	v_exp_f32_e32 v99, v99
	s_waitcnt lgkmcnt(5)
	v_mfma_f32_32x32x16_bf16 v[32:47], v[198:201], v[242:245], v[32:47]
	ds_read_b128 v[198:201], v83 offset:17504
	v_cmp_lt_f32_e32 vcc, s18, v14
	v_add_f32_e32 v0, v13, v0
	s_nop 0
	v_cndmask_b32_e32 v14, 0, v99, vcc
	v_fmamk_f32 v99, v15, 0x3e0293ee, v106
	v_exp_f32_e32 v99, v99
	v_cmp_lt_f32_e32 vcc, s18, v15
	v_add_f32_e32 v0, v14, v0
	s_nop 0
	v_cndmask_b32_e32 v15, 0, v99, vcc
	v_fmamk_f32 v99, v80, 0x3e0293ee, v106
	s_waitcnt lgkmcnt(5)
	v_mfma_f32_32x32x16_bf16 v[16:31], v[202:205], v[242:245], v[16:31]
	ds_read_b128 v[202:205], v83 offset:22112
	v_exp_f32_e32 v99, v99
	v_cmp_lt_f32_e32 vcc, s18, v80
	v_add_f32_e32 v0, v15, v0
	s_nop 0
	v_cndmask_b32_e32 v80, 0, v99, vcc
	v_fmamk_f32 v99, v81, 0x3e0293ee, v106
	v_exp_f32_e32 v99, v99
	v_cmp_lt_f32_e32 vcc, s18, v81
	v_add_f32_e32 v0, v80, v0
	s_nop 0
	v_cndmask_b32_e32 v81, 0, v99, vcc
	s_nop 0
	v_cvt_pk_bf16_f32 v242, v10, v11
	v_cvt_pk_bf16_f32 v243, v12, v13
	v_cvt_pk_bf16_f32 v244, v14, v15
	v_cvt_pk_bf16_f32 v245, v80, v81
	s_nop 1
	s_waitcnt lgkmcnt(5)
	v_mfma_f32_32x32x16_bf16 v[64:79], v[210:213], v[242:245], v[64:79]
	ds_read_b128 v[210:213], v83 offset:26720
	v_add_f32_e32 v99, v81, v0
	v_fmamk_f32 v0, v98, 0x3e0293ee, v106
	v_exp_f32_e32 v0, v0
	v_cmp_lt_f32_e32 vcc, s18, v98
	s_nop 1
	v_cndmask_b32_e32 v0, 0, v0, vcc
	v_add_f32_e32 v98, v0, v99
	v_fmamk_f32 v99, v3, 0x3e0293ee, v106
	v_exp_f32_e32 v99, v99
	v_cmp_lt_f32_e32 vcc, s18, v3
	s_nop 1
	v_cndmask_b32_e32 v3, 0, v99, vcc
	s_waitcnt lgkmcnt(5)
	v_mfma_f32_32x32x16_bf16 v[48:63], v[214:217], v[242:245], v[48:63]
	ds_read_b128 v[214:217], v83 offset:31328
	v_fmamk_f32 v99, v4, 0x3e0293ee, v106
	v_exp_f32_e32 v99, v99
	v_cmp_lt_f32_e32 vcc, s18, v4
	v_add_f32_e32 v98, v3, v98
	s_nop 0
	v_cndmask_b32_e32 v4, 0, v99, vcc
	v_fmamk_f32 v99, v5, 0x3e0293ee, v106
	v_exp_f32_e32 v99, v99
	v_cmp_lt_f32_e32 vcc, s18, v5
	v_add_f32_e32 v98, v4, v98
	s_nop 0
	v_cndmask_b32_e32 v5, 0, v99, vcc
	s_waitcnt lgkmcnt(5)
	v_mfma_f32_32x32x16_bf16 v[32:47], v[218:221], v[242:245], v[32:47]
	v_fmamk_f32 v99, v6, 0x3e0293ee, v106
	v_exp_f32_e32 v99, v99
	v_cmp_lt_f32_e32 vcc, s18, v6
	v_add_f32_e32 v98, v5, v98
	s_nop 0
	v_cndmask_b32_e32 v6, 0, v99, vcc
	v_fmamk_f32 v99, v7, 0x3e0293ee, v106
	v_exp_f32_e32 v99, v99
	v_cmp_lt_f32_e32 vcc, s18, v7
	v_add_f32_e32 v98, v6, v98
	s_nop 0
	v_cndmask_b32_e32 v7, 0, v99, vcc
	s_waitcnt lgkmcnt(4)
	v_mfma_f32_32x32x16_bf16 v[16:31], v[226:229], v[242:245], v[16:31]
	v_fmamk_f32 v99, v8, 0x3e0293ee, v106
	v_exp_f32_e32 v99, v99
	v_cmp_lt_f32_e32 vcc, s18, v8
	v_fmac_f32_e32 v106, 0x3e0293ee, v9
	v_add_f32_e32 v98, v7, v98
	v_cndmask_b32_e32 v8, 0, v99, vcc
	v_exp_f32_e32 v99, v106
	v_cmp_lt_f32_e32 vcc, s18, v9
	v_add_f32_e32 v98, v8, v98
	s_nop 0
	v_cndmask_b32_e32 v9, 0, v99, vcc
	s_nop 0
	v_cvt_pk_bf16_f32 v242, v0, v3
	v_cvt_pk_bf16_f32 v243, v4, v5
	v_cvt_pk_bf16_f32 v244, v6, v7
	v_cvt_pk_bf16_f32 v245, v8, v9
	s_nop 1
	s_waitcnt lgkmcnt(3)
	v_mfma_f32_32x32x16_bf16 v[64:79], v[198:201], v[242:245], v[64:79]
	v_add_f32_e32 v98, v9, v98
	s_waitcnt lgkmcnt(2)
	v_mfma_f32_32x32x16_bf16 v[48:63], v[202:205], v[242:245], v[48:63]
	v_add_f32_e32 v161, v98, v161
	s_waitcnt lgkmcnt(1)
	v_mfma_f32_32x32x16_bf16 v[32:47], v[210:213], v[242:245], v[32:47]
	s_waitcnt lgkmcnt(0)
	v_mfma_f32_32x32x16_bf16 v[16:31], v[214:217], v[242:245], v[16:31]

; #define MFMA32(a, b, c) __builtin_amdgcn_mfma_f32_32x32x16_bf16((a), (b), (c), 0, 0, 0)
; template <int DQK, int MODE>
; DI void attn_core(const u16* __restrict__ Qg, int ldq, const u16* __restrict__ Kg, int ldk, const u16* __restrict__ Vtg,
;                   const u64* __restrict__ maskg, int q0, float scale, char* smem, int* sflags, f32x16 (&o)[4], float& l_run) {
;     ...
;       for (int kt = 0; kt < 2; ++kt)
; #pragma unroll
;         for (int i = 0; i < 16; ++i) {
;           float pv = __builtin_amdgcn_exp2f(__builtin_fmaf(s[kt][i], sc, msc));
;           if (MODE == 1) pv = (s[kt][i] > -1e29f) ? pv : 0.f;
;           s[kt][i] = pv;
;           ls += pv;
;         }
;     ...
; #pragma unroll
;     for (int kt = 0; kt < 2; ++kt)
; #pragma unroll
;       for (int sb = 0; sb < 2; ++sb) {
;         const bf16x8 pf = pack8(s[kt][8 * sb + 0], s[kt][8 * sb + 1], s[kt][8 * sb + 2], s[kt][8 * sb + 3],
;                                 s[kt][8 * sb + 4], s[kt][8 * sb + 5], s[kt][8 * sb + 6], s[kt][8 * sb + 7]);
; #pragma unroll
;         for (int t = 0; t < 4; ++t) {
;           const bf16x8 vf = *(const bf16x8*)(Vs + (32 * t + l31) * 72 + 32 * kt + 16 * sb + hh * 8);
;           o[t] = MFMA32(vf, pf, o[t]);
;         }
;       }
.LBB0_163:
	v_mul_f32_e32 v0, 0xbe0293ee, v86
	v_fmamk_f32 v86, v121, 0x3e0293ee, v0
	v_exp_f32_e32 v86, v86
	v_fmamk_f32 v89, v118, 0x3e0293ee, v0
	v_exp_f32_e32 v89, v89
	v_cmp_lt_f32_e32 vcc, s18, v121
	v_fmamk_f32 v96, v116, 0x3e0293ee, v0
	v_exp_f32_e32 v96, v96
	v_cndmask_b32_e32 v86, 0, v86, vcc
	v_cmp_lt_f32_e32 vcc, s18, v118
	v_add_f32_e32 v90, 0, v86
	v_fmamk_f32 v97, v14, 0x3e0293ee, v0
	v_cndmask_b32_e32 v89, 0, v89, vcc
	v_add_f32_e32 v93, v89, v90
	v_fmamk_f32 v90, v120, 0x3e0293ee, v0
	v_exp_f32_e32 v90, v90
	v_cmp_lt_f32_e32 vcc, s18, v120
	v_exp_f32_e32 v97, v97
	v_fmamk_f32 v103, v15, 0x3e0293ee, v0
	v_cndmask_b32_e32 v90, 0, v90, vcc
	v_add_f32_e32 v94, v90, v93
	v_fmamk_f32 v93, v119, 0x3e0293ee, v0
	v_exp_f32_e32 v93, v93
	v_cmp_lt_f32_e32 vcc, s18, v119
	v_exp_f32_e32 v103, v103
	s_nop 0
	v_cndmask_b32_e32 v93, 0, v93, vcc
	v_add_f32_e32 v95, v93, v94
	v_fmamk_f32 v94, v122, 0x3e0293ee, v0
	v_exp_f32_e32 v94, v94
	v_cmp_lt_f32_e32 vcc, s18, v122
	s_nop 1
	v_cndmask_b32_e32 v94, 0, v94, vcc
	v_cmp_lt_f32_e32 vcc, s18, v116
	v_add_f32_e32 v95, v94, v95
	s_nop 0
	v_cndmask_b32_e32 v98, 0, v96, vcc
	v_fmamk_f32 v96, v117, 0x3e0293ee, v0
	v_exp_f32_e32 v96, v96
	v_cmp_lt_f32_e32 vcc, s18, v117
	v_add_f32_e32 v95, v98, v95
	s_nop 0
	v_cndmask_b32_e32 v99, 0, v96, vcc
	v_fmamk_f32 v96, v115, 0x3e0293ee, v0
	v_exp_f32_e32 v96, v96
	v_cmp_lt_f32_e32 vcc, s18, v115
	v_add_f32_e32 v95, v99, v95
	s_nop 0
	v_cndmask_b32_e32 v100, 0, v96, vcc
	v_fmamk_f32 v96, v85, 0x3e0293ee, v0
	v_exp_f32_e32 v96, v96
	v_cmp_lt_f32_e32 vcc, s18, v85
	v_add_f32_e32 v95, v100, v95
	s_nop 0
	v_cndmask_b32_e32 v85, 0, v96, vcc
	v_fmamk_f32 v96, v87, 0x3e0293ee, v0
	v_exp_f32_e32 v96, v96
	v_cmp_lt_f32_e32 vcc, s18, v87
	v_add_f32_e32 v95, v85, v95
	s_nop 0
	v_cndmask_b32_e32 v87, 0, v96, vcc
	v_fmamk_f32 v96, v88, 0x3e0293ee, v0
	v_exp_f32_e32 v96, v96
	v_cmp_lt_f32_e32 vcc, s18, v88
	v_add_f32_e32 v95, v87, v95
	s_nop 0
	v_cndmask_b32_e32 v88, 0, v96, vcc
	v_fmamk_f32 v96, v91, 0x3e0293ee, v0
	v_exp_f32_e32 v96, v96
	v_cmp_lt_f32_e32 vcc, s18, v91
	v_add_f32_e32 v95, v88, v95
	s_nop 0
	v_cndmask_b32_e32 v91, 0, v96, vcc
	v_fmamk_f32 v96, v92, 0x3e0293ee, v0
	v_exp_f32_e32 v96, v96
	v_cmp_lt_f32_e32 vcc, s18, v92
	v_add_f32_e32 v95, v91, v95
	s_nop 0
	v_cndmask_b32_e32 v92, 0, v96, vcc
	v_add_f32_e32 v96, v92, v95
	v_fmamk_f32 v95, v13, 0x3e0293ee, v0
	v_exp_f32_e32 v95, v95
	v_cmp_lt_f32_e32 vcc, s18, v13
	s_nop 1
	v_cndmask_b32_e32 v95, 0, v95, vcc
	v_add_f32_e32 v13, v95, v96
	v_fmamk_f32 v96, v113, 0x3e0293ee, v0
	v_exp_f32_e32 v96, v96
	v_cmp_lt_f32_e32 vcc, s18, v113
	s_nop 1
	v_cndmask_b32_e32 v96, 0, v96, vcc
	v_cmp_lt_f32_e32 vcc, s18, v14
	v_add_f32_e32 v13, v96, v13
	s_nop 0
	v_cndmask_b32_e32 v97, 0, v97, vcc
	v_add_f32_e32 v14, v97, v13
	v_fmamk_f32 v13, v114, 0x3e0293ee, v0
	v_exp_f32_e32 v13, v13
	v_cmp_lt_f32_e32 vcc, s18, v114
	s_nop 1
	v_cndmask_b32_e32 v13, 0, v13, vcc
	v_add_f32_e32 v102, v13, v14
	v_fmamk_f32 v14, v112, 0x3e0293ee, v0
	v_exp_f32_e32 v14, v14
	v_cmp_lt_f32_e32 vcc, s18, v112
	s_nop 1
	v_cndmask_b32_e32 v14, 0, v14, vcc
	v_cmp_lt_f32_e32 vcc, s18, v15
	v_add_f32_e32 v102, v14, v102
	s_nop 0
	v_cndmask_b32_e32 v15, 0, v103, vcc
	v_fmamk_f32 v103, v80, 0x3e0293ee, v0
	v_exp_f32_e32 v103, v103
	v_cmp_lt_f32_e32 vcc, s18, v80
	v_add_f32_e32 v102, v15, v102
	s_nop 0
	v_cndmask_b32_e32 v80, 0, v103, vcc
	v_fmamk_f32 v103, v81, 0x3e0293ee, v0
	v_exp_f32_e32 v103, v103
	v_cmp_lt_f32_e32 vcc, s18, v81
	v_add_f32_e32 v102, v80, v102
	s_nop 0
	v_cndmask_b32_e32 v81, 0, v103, vcc
	v_fmamk_f32 v103, v82, 0x3e0293ee, v0
	v_exp_f32_e32 v103, v103
	v_cmp_lt_f32_e32 vcc, s18, v82
	v_add_f32_e32 v102, v81, v102
	s_nop 0
	v_cndmask_b32_e32 v82, 0, v103, vcc
	v_fmamk_f32 v103, v83, 0x3e0293ee, v0
	v_exp_f32_e32 v103, v103
	v_cmp_lt_f32_e32 vcc, s18, v83
	v_add_f32_e32 v102, v82, v102
	s_nop 0
	v_cndmask_b32_e32 v83, 0, v103, vcc
	v_fmamk_f32 v103, v84, 0x3e0293ee, v0
	v_exp_f32_e32 v103, v103
	v_cmp_lt_f32_e32 vcc, s18, v84
	v_add_f32_e32 v102, v83, v102
	s_nop 0
	v_cndmask_b32_e32 v84, 0, v103, vcc
	v_fmamk_f32 v103, v5, 0x3e0293ee, v0
	v_exp_f32_e32 v103, v103
	v_cmp_lt_f32_e32 vcc, s18, v5
	v_add_f32_e32 v102, v84, v102
	s_nop 0
	v_cndmask_b32_e32 v5, 0, v103, vcc
	v_fmamk_f32 v103, v6, 0x3e0293ee, v0
	v_exp_f32_e32 v103, v103
	v_cmp_lt_f32_e32 vcc, s18, v6
	v_add_f32_e32 v102, v5, v102
	s_nop 0
	v_cndmask_b32_e32 v6, 0, v103, vcc
	v_fmamk_f32 v103, v7, 0x3e0293ee, v0
	v_exp_f32_e32 v103, v103
	v_cmp_lt_f32_e32 vcc, s18, v7
	v_add_f32_e32 v102, v6, v102
	s_nop 0
	v_cndmask_b32_e32 v7, 0, v103, vcc
	v_fmamk_f32 v103, v8, 0x3e0293ee, v0
	v_exp_f32_e32 v103, v103
	v_cmp_lt_f32_e32 vcc, s18, v8
	v_add_f32_e32 v102, v7, v102
	s_nop 0
	v_cndmask_b32_e32 v8, 0, v103, vcc
	v_fmamk_f32 v103, v9, 0x3e0293ee, v0
	v_exp_f32_e32 v103, v103
	v_cmp_lt_f32_e32 vcc, s18, v9
	v_add_f32_e32 v102, v8, v102
	s_nop 0
	v_cndmask_b32_e32 v9, 0, v103, vcc
	v_fmamk_f32 v103, v10, 0x3e0293ee, v0
	v_exp_f32_e32 v103, v103
	v_cmp_lt_f32_e32 vcc, s18, v10
	v_add_f32_e32 v102, v9, v102
	s_nop 0
	v_cndmask_b32_e32 v10, 0, v103, vcc
	v_fmamk_f32 v103, v11, 0x3e0293ee, v0
	v_exp_f32_e32 v103, v103
	v_fmac_f32_e32 v0, 0x3e0293ee, v12
	v_exp_f32_e32 v0, v0
	v_cmp_lt_f32_e32 vcc, s18, v11
	v_add_f32_e32 v102, v10, v102
	s_nop 0
	v_cndmask_b32_e32 v11, 0, v103, vcc
	v_cmp_lt_f32_e32 vcc, s18, v12
	v_add_f32_e32 v102, v11, v102
	s_nop 0
	v_cndmask_b32_e32 v12, 0, v0, vcc
	v_add_f32_e32 v0, v12, v102
	s_nop 0
	v_cvt_pk_bf16_f32 v242, v86, v89
	v_cvt_pk_bf16_f32 v243, v90, v93
	v_cvt_pk_bf16_f32 v244, v94, v98
	v_cvt_pk_bf16_f32 v245, v99, v100
	s_nop 1
	v_add_u32_e32 v86, v174, v175
	v_add_f32_e32 v0, v0, v101
	ds_read_b128 v[102:105], v86 offset:17408
	ds_read_b128 v[110:113], v86 offset:22016
	ds_read_b128 v[114:117], v86 offset:26624
	ds_read_b128 v[118:121], v86 offset:31232
	ds_read_b128 v[122:125], v86 offset:17440
	ds_read_b128 v[126:129], v86 offset:22048
	s_waitcnt lgkmcnt(5)
; #define MFMA32(a, b, c) __builtin_amdgcn_mfma_f32_32x32x16_bf16((a), (b), (c), 0, 0, 0)
; template <int DQK, int MODE>
; DI void attn_core(const u16* __restrict__ Qg, int ldq, const u16* __restrict__ Kg, int ldk, const u16* __restrict__ Vtg,
;                   const u64* __restrict__ maskg, int q0, float scale, char* smem, int* sflags, f32x16 (&o)[4], float& l_run) {
;     ...
; #pragma unroll
;     for (int kt = 0; kt < 2; ++kt)
; #pragma unroll
;       for (int sb = 0; sb < 2; ++sb) {
;         const bf16x8 pf = pack8(s[kt][8 * sb + 0], s[kt][8 * sb + 1], s[kt][8 * sb + 2], s[kt][8 * sb + 3],
;                                 s[kt][8 * sb + 4], s[kt][8 * sb + 5], s[kt][8 * sb + 6], s[kt][8 * sb + 7]);
; #pragma unroll
;         for (int t = 0; t < 4; ++t) {
;           const bf16x8 vf = *(const bf16x8*)(Vs + (32 * t + l31) * 72 + 32 * kt + 16 * sb + hh * 8);
;           o[t] = MFMA32(vf, pf, o[t]);
;         }
;       }
	v_mfma_f32_32x32x16_bf16 v[64:79], v[102:105], v[242:245], v[64:79]
	ds_read_b128 v[102:105], v86 offset:26656
	s_waitcnt lgkmcnt(5)
	v_mfma_f32_32x32x16_bf16 v[48:63], v[110:113], v[242:245], v[48:63]
	ds_read_b128 v[110:113], v86 offset:31264
	s_waitcnt lgkmcnt(5)
	v_mfma_f32_32x32x16_bf16 v[32:47], v[114:117], v[242:245], v[32:47]
	ds_read_b128 v[114:117], v86 offset:17472
	s_waitcnt lgkmcnt(5)
	v_mfma_f32_32x32x16_bf16 v[16:31], v[118:121], v[242:245], v[16:31]
	ds_read_b128 v[118:121], v86 offset:22080
	s_nop 0
	v_cvt_pk_bf16_f32 v242, v85, v87
	v_cvt_pk_bf16_f32 v243, v88, v91
	v_cvt_pk_bf16_f32 v244, v92, v95
	v_cvt_pk_bf16_f32 v245, v96, v97
	s_nop 1
	s_waitcnt lgkmcnt(5)
	v_mfma_f32_32x32x16_bf16 v[64:79], v[122:125], v[242:245], v[64:79]
	ds_read_b128 v[122:125], v86 offset:26688
	s_waitcnt lgkmcnt(5)
	v_mfma_f32_32x32x16_bf16 v[48:63], v[126:129], v[242:245], v[48:63]
	ds_read_b128 v[126:129], v86 offset:31296
	s_waitcnt lgkmcnt(5)
	v_mfma_f32_32x32x16_bf16 v[32:47], v[102:105], v[242:245], v[32:47]
	ds_read_b128 v[102:105], v86 offset:17504
	s_waitcnt lgkmcnt(5)
	v_mfma_f32_32x32x16_bf16 v[16:31], v[110:113], v[242:245], v[16:31]
	ds_read_b128 v[110:113], v86 offset:22112
	s_nop 0
	v_cvt_pk_bf16_f32 v242, v13, v14
	v_cvt_pk_bf16_f32 v243, v15, v80
	v_cvt_pk_bf16_f32 v244, v81, v82
	v_cvt_pk_bf16_f32 v245, v83, v84
	s_nop 1
	s_waitcnt lgkmcnt(5)
	v_mfma_f32_32x32x16_bf16 v[64:79], v[114:117], v[242:245], v[64:79]
	ds_read_b128 v[114:117], v86 offset:26720
	s_waitcnt lgkmcnt(5)
	v_mfma_f32_32x32x16_bf16 v[48:63], v[118:121], v[242:245], v[48:63]
	ds_read_b128 v[118:121], v86 offset:31328
	s_waitcnt lgkmcnt(5)
	v_mfma_f32_32x32x16_bf16 v[32:47], v[122:125], v[242:245], v[32:47]
	s_waitcnt lgkmcnt(4)
	v_mfma_f32_32x32x16_bf16 v[16:31], v[126:129], v[242:245], v[16:31]
	s_nop 0
	v_cvt_pk_bf16_f32 v242, v5, v6
	v_cvt_pk_bf16_f32 v243, v7, v8
	v_cvt_pk_bf16_f32 v244, v9, v10
	v_cvt_pk_bf16_f32 v245, v11, v12
	s_nop 1
	s_waitcnt lgkmcnt(3)
	v_mfma_f32_32x32x16_bf16 v[64:79], v[102:105], v[242:245], v[64:79]
	s_waitcnt lgkmcnt(2)
	v_mfma_f32_32x32x16_bf16 v[48:63], v[110:113], v[242:245], v[48:63]
	s_waitcnt lgkmcnt(1)
	v_mfma_f32_32x32x16_bf16 v[32:47], v[114:117], v[242:245], v[32:47]
	s_waitcnt lgkmcnt(0)
	v_mfma_f32_32x32x16_bf16 v[16:31], v[118:121], v[242:245], v[16:31]

; #define MFMA32(a, b, c) __builtin_amdgcn_mfma_f32_32x32x16_bf16((a), (b), (c), 0, 0, 0)
; template <int DQK, int MODE>
; DI void attn_core(const u16* __restrict__ Qg, int ldq, const u16* __restrict__ Kg, int ldk, const u16* __restrict__ Vtg,
;                   const u64* __restrict__ maskg, int q0, float scale, char* smem, int* sflags, f32x16 (&o)[4], float& l_run) {
;     ...
;       for (int kt = 0; kt < 2; ++kt)
; #pragma unroll
;         for (int i = 0; i < 16; ++i) {
;           float pv = __builtin_amdgcn_exp2f(__builtin_fmaf(s[kt][i], sc, msc));
;           if (MODE == 1) pv = (s[kt][i] > -1e29f) ? pv : 0.f;
;           s[kt][i] = pv;
;           ls += pv;
;         }
;     ...
; #pragma unroll
;     for (int kt = 0; kt < 2; ++kt)
; #pragma unroll
;       for (int sb = 0; sb < 2; ++sb) {
;         const bf16x8 pf = pack8(s[kt][8 * sb + 0], s[kt][8 * sb + 1], s[kt][8 * sb + 2], s[kt][8 * sb + 3],
;                                 s[kt][8 * sb + 4], s[kt][8 * sb + 5], s[kt][8 * sb + 6], s[kt][8 * sb + 7]);
; #pragma unroll
;         for (int t = 0; t < 4; ++t) {
;           const bf16x8 vf = *(const bf16x8*)(Vs + (32 * t + l31) * 72 + 32 * kt + 16 * sb + hh * 8);
;           o[t] = MFMA32(vf, pf, o[t]);
;         }
;       }
.LBB0_174:
	v_add_u32_e32 v222, v211, v212
	v_mul_f32_e32 v9, 0xbdd53b94, v2
	v_fmamk_f32 v0, v80, 0x3dd53b94, v9
	v_exp_f32_e32 v198, v0
	v_fmamk_f32 v3, v81, 0x3dd53b94, v9
	v_exp_f32_e32 v199, v3
	v_fmamk_f32 v3, v82, 0x3dd53b94, v9
	v_exp_f32_e32 v200, v3
	v_fmamk_f32 v3, v83, 0x3dd53b94, v9
	v_exp_f32_e32 v201, v3
	v_fmamk_f32 v3, v84, 0x3dd53b94, v9
	v_add_f32_e32 v0, 0, v198
	v_exp_f32_e32 v202, v3
	v_fmamk_f32 v3, v85, 0x3dd53b94, v9
	v_add_f32_e32 v0, v199, v0
	v_exp_f32_e32 v203, v3
	v_fmamk_f32 v3, v86, 0x3dd53b94, v9
	v_add_f32_e32 v0, v200, v0
	v_exp_f32_e32 v86, v3
	v_fmamk_f32 v3, v87, 0x3dd53b94, v9
	v_add_f32_e32 v0, v201, v0
	v_exp_f32_e32 v87, v3
	s_nop 0
	v_cvt_pk_bf16_f32 v244, v198, v199
	v_cvt_pk_bf16_f32 v245, v200, v201
	v_cvt_pk_bf16_f32 v246, v202, v203
	v_cvt_pk_bf16_f32 v247, v86, v87
	s_nop 1
	ds_read_b128 v[198:201], v222 offset:25600
	ds_read_b128 v[232:235], v222 offset:30208
	ds_read_b128 v[236:239], v222 offset:34816
	ds_read_b128 v[240:243], v222 offset:39424
	s_waitcnt lgkmcnt(3)
	v_mfma_f32_32x32x16_bf16 v[64:79], v[198:201], v[244:247], v[64:79]
	ds_read_b128 v[198:201], v222 offset:25632
	v_fmamk_f32 v3, v88, 0x3dd53b94, v9
	v_add_f32_e32 v0, v202, v0
	v_exp_f32_e32 v204, v3
	v_fmamk_f32 v3, v89, 0x3dd53b94, v9
	v_add_f32_e32 v0, v203, v0
	v_exp_f32_e32 v205, v3
	s_waitcnt lgkmcnt(3)
	v_mfma_f32_32x32x16_bf16 v[48:63], v[232:235], v[244:247], v[48:63]
	ds_read_b128 v[232:235], v222 offset:30240
	v_fmamk_f32 v3, v90, 0x3dd53b94, v9
	v_add_f32_e32 v0, v86, v0
	v_exp_f32_e32 v90, v3
	v_fmamk_f32 v3, v91, 0x3dd53b94, v9
	v_add_f32_e32 v0, v87, v0
	v_exp_f32_e32 v91, v3
	s_waitcnt lgkmcnt(3)
	v_mfma_f32_32x32x16_bf16 v[32:47], v[236:239], v[244:247], v[32:47]
	ds_read_b128 v[236:239], v222 offset:34848
	v_fmamk_f32 v3, v92, 0x3dd53b94, v9
	v_add_f32_e32 v0, v204, v0
	v_exp_f32_e32 v92, v3
	v_fmamk_f32 v3, v93, 0x3dd53b94, v9
	v_add_f32_e32 v0, v205, v0
	v_exp_f32_e32 v93, v3
	s_waitcnt lgkmcnt(3)
	v_mfma_f32_32x32x16_bf16 v[16:31], v[240:243], v[244:247], v[16:31]
	ds_read_b128 v[240:243], v222 offset:39456
	v_fmamk_f32 v3, v94, 0x3dd53b94, v9
	v_add_f32_e32 v0, v90, v0
	v_exp_f32_e32 v94, v3
	v_fmamk_f32 v3, v95, 0x3dd53b94, v9
	v_add_f32_e32 v0, v91, v0
	v_exp_f32_e32 v95, v3
	s_nop 0
	v_cvt_pk_bf16_f32 v244, v204, v205
	v_cvt_pk_bf16_f32 v245, v90, v91
	v_cvt_pk_bf16_f32 v246, v92, v93
	v_cvt_pk_bf16_f32 v247, v94, v95
	s_nop 1
	s_waitcnt lgkmcnt(3)
	v_mfma_f32_32x32x16_bf16 v[64:79], v[198:201], v[244:247], v[64:79]
	ds_read_b128 v[198:201], v222 offset:25664
	v_fmamk_f32 v3, v96, 0x3dd53b94, v9
	v_add_f32_e32 v0, v92, v0
	v_exp_f32_e32 v10, v3
	v_fmamk_f32 v3, v97, 0x3dd53b94, v9
	v_add_f32_e32 v0, v93, v0
	v_exp_f32_e32 v11, v3
	s_waitcnt lgkmcnt(3)
	v_mfma_f32_32x32x16_bf16 v[48:63], v[232:235], v[244:247], v[48:63]
	ds_read_b128 v[232:235], v222 offset:30272
	v_fmamk_f32 v3, v98, 0x3dd53b94, v9
	v_add_f32_e32 v0, v94, v0
	v_exp_f32_e32 v12, v3
	v_fmamk_f32 v3, v99, 0x3dd53b94, v9
	v_add_f32_e32 v0, v95, v0
	v_exp_f32_e32 v13, v3
	s_waitcnt lgkmcnt(3)
	v_mfma_f32_32x32x16_bf16 v[32:47], v[236:239], v[244:247], v[32:47]
	ds_read_b128 v[236:239], v222 offset:34880
	v_fmamk_f32 v3, v100, 0x3dd53b94, v9
	v_add_f32_e32 v0, v10, v0
	v_exp_f32_e32 v14, v3
	v_fmamk_f32 v3, v101, 0x3dd53b94, v9
	v_add_f32_e32 v0, v11, v0
	v_exp_f32_e32 v15, v3
	s_waitcnt lgkmcnt(3)
	v_mfma_f32_32x32x16_bf16 v[16:31], v[240:243], v[244:247], v[16:31]
	ds_read_b128 v[240:243], v222 offset:39488
	v_fmamk_f32 v3, v102, 0x3dd53b94, v9
	v_add_f32_e32 v0, v12, v0
	v_exp_f32_e32 v80, v3
	v_fmamk_f32 v3, v103, 0x3dd53b94, v9
	v_add_f32_e32 v0, v13, v0
	v_exp_f32_e32 v81, v3
	s_nop 0
	v_cvt_pk_bf16_f32 v244, v10, v11
	v_cvt_pk_bf16_f32 v245, v12, v13
	v_cvt_pk_bf16_f32 v246, v14, v15
	v_cvt_pk_bf16_f32 v247, v80, v81
	s_nop 1
	s_waitcnt lgkmcnt(3)
	v_mfma_f32_32x32x16_bf16 v[64:79], v[198:201], v[244:247], v[64:79]
	ds_read_b128 v[198:201], v222 offset:25696
	v_add_f32_e32 v0, v14, v0
	v_add_f32_e32 v0, v15, v0
	v_add_f32_e32 v0, v80, v0
	v_add_f32_e32 v3, v81, v0
	v_fmamk_f32 v0, v104, 0x3dd53b94, v9
	v_exp_f32_e32 v0, v0
	s_nop 0
	v_mov_b32_e32 v230, v2
	v_add_f32_e32 v4, v0, v3
	s_waitcnt lgkmcnt(3)
	v_mfma_f32_32x32x16_bf16 v[48:63], v[232:235], v[244:247], v[48:63]
	ds_read_b128 v[232:235], v222 offset:30304
	v_fmamk_f32 v3, v105, 0x3dd53b94, v9
	v_exp_f32_e32 v3, v3
	s_nop 0
	v_add_f32_e32 v5, v3, v4
	v_fmamk_f32 v4, v106, 0x3dd53b94, v9
	v_exp_f32_e32 v4, v4
	s_nop 0
	v_add_f32_e32 v6, v4, v5
	v_fmamk_f32 v5, v107, 0x3dd53b94, v9
	s_waitcnt lgkmcnt(3)
	v_mfma_f32_32x32x16_bf16 v[32:47], v[236:239], v[244:247], v[32:47]
	ds_read_b128 v[236:239], v222 offset:34912
	v_exp_f32_e32 v5, v5
	s_nop 0
	v_add_f32_e32 v7, v5, v6
	v_fmamk_f32 v6, v108, 0x3dd53b94, v9
	v_exp_f32_e32 v6, v6
	s_nop 0
	v_add_f32_e32 v8, v6, v7
	v_fmamk_f32 v7, v109, 0x3dd53b94, v9
	v_exp_f32_e32 v7, v7
	s_waitcnt lgkmcnt(3)
	v_mfma_f32_32x32x16_bf16 v[16:31], v[240:243], v[244:247], v[16:31]
	ds_read_b128 v[240:243], v222 offset:39520
	s_nop 0
	v_add_f32_e32 v82, v7, v8
	v_fmamk_f32 v8, v110, 0x3dd53b94, v9
	v_exp_f32_e32 v8, v8
	v_fmac_f32_e32 v9, 0x3dd53b94, v111
	v_exp_f32_e32 v9, v9
	s_nop 0
	v_cvt_pk_bf16_f32 v244, v0, v3
	v_cvt_pk_bf16_f32 v245, v4, v5
	v_cvt_pk_bf16_f32 v246, v6, v7
	v_cvt_pk_bf16_f32 v247, v8, v9
	s_nop 1
	s_waitcnt lgkmcnt(3)
	v_mfma_f32_32x32x16_bf16 v[64:79], v[198:201], v[244:247], v[64:79]
	v_add_f32_e32 v82, v8, v82
	s_waitcnt lgkmcnt(2)
	v_mfma_f32_32x32x16_bf16 v[48:63], v[232:235], v[244:247], v[48:63]
	v_add_f32_e32 v82, v9, v82
	s_waitcnt lgkmcnt(1)
	v_mfma_f32_32x32x16_bf16 v[32:47], v[236:239], v[244:247], v[32:47]
	v_add_f32_e32 v210, v82, v210
	s_waitcnt lgkmcnt(0)
	v_mfma_f32_32x32x16_bf16 v[16:31], v[240:243], v[244:247], v[16:31]

; #define MFMA32(a, b, c) __builtin_amdgcn_mfma_f32_32x32x16_bf16((a), (b), (c), 0, 0, 0)
; template <int DQK, int MODE>
; DI void attn_core(const u16* __restrict__ Qg, int ldq, const u16* __restrict__ Kg, int ldk, const u16* __restrict__ Vtg,
;                   const u64* __restrict__ maskg, int q0, float scale, char* smem, int* sflags, f32x16 (&o)[4], float& l_run) {
;     ...
;       for (int kt = 0; kt < 2; ++kt)
; #pragma unroll
;         for (int i = 0; i < 16; ++i) {
;           float pv = __builtin_amdgcn_exp2f(__builtin_fmaf(s[kt][i], sc, msc));
;           if (MODE == 1) pv = (s[kt][i] > -1e29f) ? pv : 0.f;
;           s[kt][i] = pv;
;           ls += pv;
;         }
;     ...
; #pragma unroll
;     for (int kt = 0; kt < 2; ++kt)
; #pragma unroll
;       for (int sb = 0; sb < 2; ++sb) {
;         const bf16x8 pf = pack8(s[kt][8 * sb + 0], s[kt][8 * sb + 1], s[kt][8 * sb + 2], s[kt][8 * sb + 3],
;                                 s[kt][8 * sb + 4], s[kt][8 * sb + 5], s[kt][8 * sb + 6], s[kt][8 * sb + 7]);
; #pragma unroll
;         for (int t = 0; t < 4; ++t) {
;           const bf16x8 vf = *(const bf16x8*)(Vs + (32 * t + l31) * 72 + 32 * kt + 16 * sb + hh * 8);
;           o[t] = MFMA32(vf, pf, o[t]);
;         }
;       }
.LBB0_183:
	v_mul_f32_e32 v0, 0xbdd53b94, v5
	v_fmamk_f32 v5, v80, 0x3dd53b94, v0
	v_exp_f32_e32 v113, v5
	v_fmamk_f32 v6, v81, 0x3dd53b94, v0
	v_exp_f32_e32 v114, v6
	v_fmamk_f32 v6, v82, 0x3dd53b94, v0
	v_exp_f32_e32 v115, v6
	v_fmamk_f32 v6, v83, 0x3dd53b94, v0
	v_exp_f32_e32 v116, v6
	v_fmamk_f32 v6, v84, 0x3dd53b94, v0
	v_add_f32_e32 v5, 0, v113
	v_exp_f32_e32 v117, v6
	v_fmamk_f32 v6, v85, 0x3dd53b94, v0
	v_add_f32_e32 v5, v114, v5
	v_exp_f32_e32 v85, v6
	v_fmamk_f32 v6, v86, 0x3dd53b94, v0
	v_add_f32_e32 v5, v115, v5
	v_exp_f32_e32 v118, v6
	v_fmamk_f32 v6, v87, 0x3dd53b94, v0
	v_add_f32_e32 v5, v116, v5
	v_exp_f32_e32 v119, v6
	v_fmamk_f32 v6, v88, 0x3dd53b94, v0
	v_add_f32_e32 v5, v117, v5
	v_exp_f32_e32 v120, v6
	v_fmamk_f32 v6, v89, 0x3dd53b94, v0
	v_add_f32_e32 v5, v85, v5
	v_exp_f32_e32 v121, v6
	v_fmamk_f32 v6, v90, 0x3dd53b94, v0
	v_add_f32_e32 v5, v118, v5
	v_exp_f32_e32 v122, v6
	v_fmamk_f32 v6, v91, 0x3dd53b94, v0
	v_add_f32_e32 v5, v119, v5
	v_exp_f32_e32 v123, v6
	v_fmamk_f32 v6, v92, 0x3dd53b94, v0
	v_add_f32_e32 v5, v120, v5
	v_exp_f32_e32 v124, v6
	v_fmamk_f32 v6, v93, 0x3dd53b94, v0
	v_add_f32_e32 v5, v121, v5
	v_exp_f32_e32 v125, v6
	v_fmamk_f32 v6, v94, 0x3dd53b94, v0
	v_add_f32_e32 v5, v122, v5
	v_exp_f32_e32 v94, v6
	v_fmamk_f32 v6, v95, 0x3dd53b94, v0
	v_add_f32_e32 v5, v123, v5
	v_exp_f32_e32 v95, v6
	v_fmamk_f32 v6, v96, 0x3dd53b94, v0
	v_add_f32_e32 v5, v124, v5
	v_exp_f32_e32 v13, v6
	v_fmamk_f32 v6, v97, 0x3dd53b94, v0
	v_add_f32_e32 v5, v125, v5
	v_exp_f32_e32 v14, v6
	v_fmamk_f32 v6, v98, 0x3dd53b94, v0
	v_add_f32_e32 v5, v94, v5
	v_exp_f32_e32 v15, v6
	v_fmamk_f32 v6, v99, 0x3dd53b94, v0
	v_add_f32_e32 v5, v95, v5
	v_exp_f32_e32 v80, v6
	v_fmamk_f32 v6, v100, 0x3dd53b94, v0
	v_add_f32_e32 v5, v13, v5
	v_exp_f32_e32 v81, v6
	v_fmamk_f32 v6, v101, 0x3dd53b94, v0
	v_add_f32_e32 v5, v14, v5
	v_exp_f32_e32 v82, v6
	v_fmamk_f32 v6, v102, 0x3dd53b94, v0
	v_add_f32_e32 v5, v15, v5
	v_exp_f32_e32 v83, v6
	v_fmamk_f32 v6, v103, 0x3dd53b94, v0
	v_add_f32_e32 v5, v80, v5
	v_exp_f32_e32 v84, v6
	v_add_f32_e32 v5, v81, v5
	v_add_f32_e32 v5, v82, v5
	v_add_f32_e32 v5, v83, v5
	v_add_f32_e32 v6, v84, v5
	v_fmamk_f32 v5, v104, 0x3dd53b94, v0
	v_exp_f32_e32 v5, v5
	s_nop 0
	v_add_f32_e32 v7, v5, v6
	v_fmamk_f32 v6, v105, 0x3dd53b94, v0
	v_exp_f32_e32 v6, v6
	s_nop 0
	v_add_f32_e32 v8, v6, v7
	v_fmamk_f32 v7, v106, 0x3dd53b94, v0
	v_exp_f32_e32 v7, v7
	s_nop 0
	v_add_f32_e32 v9, v7, v8
	v_fmamk_f32 v8, v107, 0x3dd53b94, v0
	v_exp_f32_e32 v8, v8
	s_nop 0
	v_add_f32_e32 v10, v8, v9
	v_fmamk_f32 v9, v108, 0x3dd53b94, v0
	v_exp_f32_e32 v9, v9
	s_nop 0
	v_add_f32_e32 v11, v9, v10
	v_fmamk_f32 v10, v109, 0x3dd53b94, v0
	v_exp_f32_e32 v10, v10
	s_nop 0
	v_add_f32_e32 v12, v10, v11
	v_fmamk_f32 v11, v110, 0x3dd53b94, v0
	v_exp_f32_e32 v11, v11
	v_fmac_f32_e32 v0, 0x3dd53b94, v111
	v_add_f32_e32 v86, v11, v12
	v_exp_f32_e32 v12, v0
	s_nop 0
	v_add_f32_e32 v0, v12, v86
	s_nop 0
	v_cvt_pk_bf16_f32 v242, v113, v114
	v_cvt_pk_bf16_f32 v243, v115, v116
	v_cvt_pk_bf16_f32 v244, v117, v85
	v_cvt_pk_bf16_f32 v245, v118, v119
	s_nop 1
	v_add_u32_e32 v85, v211, v212
	v_add_f32_e32 v0, v0, v112
	ds_read_b128 v[86:89], v85 offset:25600
	ds_read_b128 v[96:99], v85 offset:30208
	ds_read_b128 v[100:103], v85 offset:34816
	ds_read_b128 v[110:113], v85 offset:39424
	ds_read_b128 v[114:117], v85 offset:25632
	ds_read_b128 v[126:129], v85 offset:30240
	s_waitcnt lgkmcnt(5)
	v_mfma_f32_32x32x16_bf16 v[64:79], v[86:89], v[242:245], v[64:79]
	ds_read_b128 v[86:89], v85 offset:34848
	s_waitcnt lgkmcnt(5)
	v_mfma_f32_32x32x16_bf16 v[48:63], v[96:99], v[242:245], v[48:63]
	ds_read_b128 v[96:99], v85 offset:39456
	s_waitcnt lgkmcnt(5)
	v_mfma_f32_32x32x16_bf16 v[32:47], v[100:103], v[242:245], v[32:47]
	ds_read_b128 v[100:103], v85 offset:25664
	s_waitcnt lgkmcnt(5)
	v_mfma_f32_32x32x16_bf16 v[16:31], v[110:113], v[242:245], v[16:31]
	ds_read_b128 v[110:113], v85 offset:30272
	s_nop 0
	v_cvt_pk_bf16_f32 v242, v120, v121
	v_cvt_pk_bf16_f32 v243, v122, v123
	v_cvt_pk_bf16_f32 v244, v124, v125
	v_cvt_pk_bf16_f32 v245, v94, v95
	s_nop 1
	s_waitcnt lgkmcnt(5)
	v_mfma_f32_32x32x16_bf16 v[64:79], v[114:117], v[242:245], v[64:79]
	ds_read_b128 v[114:117], v85 offset:34880
	s_waitcnt lgkmcnt(5)
	v_mfma_f32_32x32x16_bf16 v[48:63], v[126:129], v[242:245], v[48:63]
	ds_read_b128 v[126:129], v85 offset:39488
	s_waitcnt lgkmcnt(5)
	v_mfma_f32_32x32x16_bf16 v[32:47], v[86:89], v[242:245], v[32:47]
	ds_read_b128 v[86:89], v85 offset:25696
	s_waitcnt lgkmcnt(5)
	v_mfma_f32_32x32x16_bf16 v[16:31], v[96:99], v[242:245], v[16:31]
	ds_read_b128 v[96:99], v85 offset:30304
	s_nop 0
	v_cvt_pk_bf16_f32 v242, v13, v14
	v_cvt_pk_bf16_f32 v243, v15, v80
	v_cvt_pk_bf16_f32 v244, v81, v82
	v_cvt_pk_bf16_f32 v245, v83, v84
	s_nop 1
	s_waitcnt lgkmcnt(5)
	v_mfma_f32_32x32x16_bf16 v[64:79], v[100:103], v[242:245], v[64:79]
	ds_read_b128 v[100:103], v85 offset:34912
	s_waitcnt lgkmcnt(5)
	v_mfma_f32_32x32x16_bf16 v[48:63], v[110:113], v[242:245], v[48:63]
	ds_read_b128 v[110:113], v85 offset:39520
	s_waitcnt lgkmcnt(5)
	v_mfma_f32_32x32x16_bf16 v[32:47], v[114:117], v[242:245], v[32:47]
	s_waitcnt lgkmcnt(4)
	v_mfma_f32_32x32x16_bf16 v[16:31], v[126:129], v[242:245], v[16:31]
	s_nop 0
	v_cvt_pk_bf16_f32 v242, v5, v6
	v_cvt_pk_bf16_f32 v243, v7, v8
	v_cvt_pk_bf16_f32 v244, v9, v10
	v_cvt_pk_bf16_f32 v245, v11, v12
	s_nop 1
	s_waitcnt lgkmcnt(3)
	v_mfma_f32_32x32x16_bf16 v[64:79], v[86:89], v[242:245], v[64:79]
	s_waitcnt lgkmcnt(2)
	v_mfma_f32_32x32x16_bf16 v[48:63], v[96:99], v[242:245], v[48:63]
	s_waitcnt lgkmcnt(1)
	v_mfma_f32_32x32x16_bf16 v[32:47], v[100:103], v[242:245], v[32:47]
	s_waitcnt lgkmcnt(0)
	v_mfma_f32_32x32x16_bf16 v[16:31], v[110:113], v[242:245], v[16:31]

; #define MFMA32(a, b, c) __builtin_amdgcn_mfma_f32_32x32x16_bf16((a), (b), (c), 0, 0, 0)
; template <int DQK, int MODE>
; DI void attn_core(const u16* __restrict__ Qg, int ldq, const u16* __restrict__ Kg, int ldk, const u16* __restrict__ Vtg,
;                   const u64* __restrict__ maskg, int q0, float scale, char* smem, int* sflags, f32x16 (&o)[4], float& l_run) {
;     ...
;       for (int kt = 0; kt < 2; ++kt)
; #pragma unroll
;         for (int i = 0; i < 16; ++i) {
;           float pv = __builtin_amdgcn_exp2f(__builtin_fmaf(s[kt][i], sc, msc));
;           if (MODE == 1) pv = (s[kt][i] > -1e29f) ? pv : 0.f;
;           s[kt][i] = pv;
;           ls += pv;
;         }
;     ...
; #pragma unroll
;     for (int kt = 0; kt < 2; ++kt)
; #pragma unroll
;       for (int sb = 0; sb < 2; ++sb) {
;         const bf16x8 pf = pack8(s[kt][8 * sb + 0], s[kt][8 * sb + 1], s[kt][8 * sb + 2], s[kt][8 * sb + 3],
;                                 s[kt][8 * sb + 4], s[kt][8 * sb + 5], s[kt][8 * sb + 6], s[kt][8 * sb + 7]);
; #pragma unroll
;         for (int t = 0; t < 4; ++t) {
;           const bf16x8 vf = *(const bf16x8*)(Vs + (32 * t + l31) * 72 + 32 * kt + 16 * sb + hh * 8);
;           o[t] = MFMA32(vf, pf, o[t]);
;         }
;       }
.LBB0_200:
	v_mul_f32_e32 v8, 0xbe38aa3b, v2
	v_fmamk_f32 v0, v96, 0x3e38aa3b, v8
	v_exp_f32_e32 v96, v0
	v_fmamk_f32 v2, v97, 0x3e38aa3b, v8
	v_exp_f32_e32 v97, v2
	v_fmamk_f32 v2, v98, 0x3e38aa3b, v8
	v_exp_f32_e32 v98, v2
	v_fmamk_f32 v2, v99, 0x3e38aa3b, v8
	v_exp_f32_e32 v99, v2
	v_fmamk_f32 v2, v100, 0x3e38aa3b, v8
	v_add_f32_e32 v0, 0, v96
	v_exp_f32_e32 v100, v2
	v_fmamk_f32 v2, v101, 0x3e38aa3b, v8
	v_add_f32_e32 v0, v97, v0
	v_exp_f32_e32 v101, v2
	v_fmamk_f32 v2, v102, 0x3e38aa3b, v8
	v_add_f32_e32 v0, v98, v0
	v_exp_f32_e32 v102, v2
	v_fmamk_f32 v2, v103, 0x3e38aa3b, v8
	v_add_f32_e32 v0, v99, v0
	v_exp_f32_e32 v103, v2
	v_fmamk_f32 v2, v104, 0x3e38aa3b, v8
	v_add_f32_e32 v0, v100, v0
	v_exp_f32_e32 v104, v2
	v_fmamk_f32 v2, v105, 0x3e38aa3b, v8
	v_add_f32_e32 v0, v101, v0
	v_exp_f32_e32 v105, v2
	v_fmamk_f32 v2, v106, 0x3e38aa3b, v8
	v_add_f32_e32 v0, v102, v0
	v_exp_f32_e32 v106, v2
	v_fmamk_f32 v2, v107, 0x3e38aa3b, v8
	v_add_f32_e32 v0, v103, v0
	v_exp_f32_e32 v107, v2
	v_fmamk_f32 v2, v108, 0x3e38aa3b, v8
	v_add_f32_e32 v0, v104, v0
	v_exp_f32_e32 v108, v2
	v_fmamk_f32 v2, v109, 0x3e38aa3b, v8
	v_add_f32_e32 v0, v105, v0
	v_exp_f32_e32 v109, v2
	v_fmamk_f32 v2, v110, 0x3e38aa3b, v8
	v_add_f32_e32 v0, v106, v0
	v_exp_f32_e32 v110, v2
	v_fmamk_f32 v2, v111, 0x3e38aa3b, v8
	v_add_f32_e32 v0, v107, v0
	v_exp_f32_e32 v111, v2
	v_fmamk_f32 v2, v80, 0x3e38aa3b, v8
	v_add_f32_e32 v0, v108, v0
	v_exp_f32_e32 v9, v2
	v_fmamk_f32 v2, v81, 0x3e38aa3b, v8
	v_add_f32_e32 v0, v109, v0
	v_exp_f32_e32 v10, v2
	v_fmamk_f32 v2, v82, 0x3e38aa3b, v8
	v_add_f32_e32 v0, v110, v0
	v_exp_f32_e32 v11, v2
	v_fmamk_f32 v2, v83, 0x3e38aa3b, v8
	v_add_f32_e32 v0, v111, v0
	v_exp_f32_e32 v12, v2
	v_fmamk_f32 v2, v84, 0x3e38aa3b, v8
	v_add_f32_e32 v0, v9, v0
	v_exp_f32_e32 v13, v2
	v_fmamk_f32 v2, v85, 0x3e38aa3b, v8
	v_add_f32_e32 v0, v10, v0
	v_exp_f32_e32 v14, v2
	v_fmamk_f32 v2, v86, 0x3e38aa3b, v8
	v_add_f32_e32 v0, v11, v0
	v_exp_f32_e32 v15, v2
	v_fmamk_f32 v2, v87, 0x3e38aa3b, v8
	v_add_f32_e32 v0, v12, v0
	v_exp_f32_e32 v80, v2
	v_add_f32_e32 v0, v13, v0
	v_add_f32_e32 v0, v14, v0
	v_add_f32_e32 v0, v15, v0
	v_add_f32_e32 v2, v80, v0
	v_fmamk_f32 v0, v88, 0x3e38aa3b, v8
	v_exp_f32_e32 v0, v0
	s_nop 0
	v_cvt_pk_bf16_f32 v244, v96, v97
	v_cvt_pk_bf16_f32 v245, v98, v99
	v_cvt_pk_bf16_f32 v246, v100, v101
	v_cvt_pk_bf16_f32 v247, v102, v103
	s_nop 1
	s_nop 0
	v_add_f32_e32 v3, v0, v2
	v_fmamk_f32 v2, v89, 0x3e38aa3b, v8
	v_exp_f32_e32 v2, v2
	s_nop 0
	v_add_f32_e32 v4, v2, v3
	v_fmamk_f32 v3, v90, 0x3e38aa3b, v8
	v_exp_f32_e32 v3, v3
	s_nop 0
	v_add_f32_e32 v5, v3, v4
	v_fmamk_f32 v4, v91, 0x3e38aa3b, v8
	v_exp_f32_e32 v4, v4
	s_nop 0
	v_add_f32_e32 v6, v4, v5
	v_fmamk_f32 v5, v92, 0x3e38aa3b, v8
	v_exp_f32_e32 v5, v5
	s_nop 0
	v_add_f32_e32 v7, v5, v6
	v_fmamk_f32 v6, v93, 0x3e38aa3b, v8
	v_exp_f32_e32 v6, v6
	s_nop 0
	v_add_f32_e32 v81, v6, v7
	v_fmamk_f32 v7, v94, 0x3e38aa3b, v8
	v_exp_f32_e32 v7, v7
	v_fmac_f32_e32 v8, 0x3e38aa3b, v95
	v_exp_f32_e32 v8, v8
	v_add_f32_e32 v81, v7, v81
	v_add_f32_e32 v81, v8, v81
	v_add_f32_e32 v143, v81, v143
	v_add_u32_e32 v81, v142, v152
	ds_read_b128 v[82:85], v81 offset:9216
	ds_read_b128 v[90:93], v81 offset:13824
	ds_read_b128 v[94:97], v81 offset:18432
	ds_read_b128 v[98:101], v81 offset:23040
	ds_read_b128 v[112:115], v81 offset:9248
	ds_read_b128 v[116:119], v81 offset:13856
	s_waitcnt lgkmcnt(5)
	v_mfma_f32_32x32x16_bf16 v[64:79], v[82:85], v[244:247], v[64:79]
	ds_read_b128 v[82:85], v81 offset:18464
	s_waitcnt lgkmcnt(5)
	v_mfma_f32_32x32x16_bf16 v[48:63], v[90:93], v[244:247], v[48:63]
	ds_read_b128 v[90:93], v81 offset:23072
	s_waitcnt lgkmcnt(5)
	v_mfma_f32_32x32x16_bf16 v[32:47], v[94:97], v[244:247], v[32:47]
	ds_read_b128 v[94:97], v81 offset:9280
	s_waitcnt lgkmcnt(5)
	v_mfma_f32_32x32x16_bf16 v[16:31], v[98:101], v[244:247], v[16:31]
	ds_read_b128 v[98:101], v81 offset:13888
	s_nop 0
	v_cvt_pk_bf16_f32 v244, v104, v105
	v_cvt_pk_bf16_f32 v245, v106, v107
	v_cvt_pk_bf16_f32 v246, v108, v109
	v_cvt_pk_bf16_f32 v247, v110, v111
	s_nop 1
	s_waitcnt lgkmcnt(5)
	v_mfma_f32_32x32x16_bf16 v[64:79], v[112:115], v[244:247], v[64:79]
	ds_read_b128 v[112:115], v81 offset:18496
	s_waitcnt lgkmcnt(5)
	v_mfma_f32_32x32x16_bf16 v[48:63], v[116:119], v[244:247], v[48:63]
	ds_read_b128 v[116:119], v81 offset:23104
	s_waitcnt lgkmcnt(5)
	v_mfma_f32_32x32x16_bf16 v[32:47], v[82:85], v[244:247], v[32:47]
	ds_read_b128 v[82:85], v81 offset:9312
	s_waitcnt lgkmcnt(5)
	v_mfma_f32_32x32x16_bf16 v[16:31], v[90:93], v[244:247], v[16:31]
	ds_read_b128 v[90:93], v81 offset:13920
	s_nop 0
	v_cvt_pk_bf16_f32 v244, v9, v10
	v_cvt_pk_bf16_f32 v245, v11, v12
	v_cvt_pk_bf16_f32 v246, v13, v14
	v_cvt_pk_bf16_f32 v247, v15, v80
	s_nop 1
	s_waitcnt lgkmcnt(5)
	v_mfma_f32_32x32x16_bf16 v[64:79], v[94:97], v[244:247], v[64:79]
	ds_read_b128 v[94:97], v81 offset:18528
	s_waitcnt lgkmcnt(5)
	v_mfma_f32_32x32x16_bf16 v[48:63], v[98:101], v[244:247], v[48:63]
	ds_read_b128 v[98:101], v81 offset:23136
	s_waitcnt lgkmcnt(5)
	v_mfma_f32_32x32x16_bf16 v[32:47], v[112:115], v[244:247], v[32:47]
	s_waitcnt lgkmcnt(4)
	v_mfma_f32_32x32x16_bf16 v[16:31], v[116:119], v[244:247], v[16:31]
	s_nop 0
	v_cvt_pk_bf16_f32 v244, v0, v2
	v_cvt_pk_bf16_f32 v245, v3, v4
	v_cvt_pk_bf16_f32 v246, v5, v6
	v_cvt_pk_bf16_f32 v247, v7, v8
	s_nop 1
	s_waitcnt lgkmcnt(3)
	v_mfma_f32_32x32x16_bf16 v[64:79], v[82:85], v[244:247], v[64:79]
	s_waitcnt lgkmcnt(2)
	v_mfma_f32_32x32x16_bf16 v[48:63], v[90:93], v[244:247], v[48:63]
	s_waitcnt lgkmcnt(1)
	v_mfma_f32_32x32x16_bf16 v[32:47], v[94:97], v[244:247], v[32:47]
	s_waitcnt lgkmcnt(0)
	v_mfma_f32_32x32x16_bf16 v[16:31], v[98:101], v[244:247], v[16:31]

; #define MFMA32(a, b, c) __builtin_amdgcn_mfma_f32_32x32x16_bf16((a), (b), (c), 0, 0, 0)
; template <int DQK, int MODE>
; DI void attn_core(const u16* __restrict__ Qg, int ldq, const u16* __restrict__ Kg, int ldk, const u16* __restrict__ Vtg,
;                   const u64* __restrict__ maskg, int q0, float scale, char* smem, int* sflags, f32x16 (&o)[4], float& l_run) {
;     ...
;       for (int kt = 0; kt < 2; ++kt)
; #pragma unroll
;         for (int i = 0; i < 16; ++i) {
;           float pv = __builtin_amdgcn_exp2f(__builtin_fmaf(s[kt][i], sc, msc));
;           if (MODE == 1) pv = (s[kt][i] > -1e29f) ? pv : 0.f;
;           s[kt][i] = pv;
;           ls += pv;
;         }
;     ...
; #pragma unroll
;     for (int kt = 0; kt < 2; ++kt)
; #pragma unroll
;       for (int sb = 0; sb < 2; ++sb) {
;         const bf16x8 pf = pack8(s[kt][8 * sb + 0], s[kt][8 * sb + 1], s[kt][8 * sb + 2], s[kt][8 * sb + 3],
;                                 s[kt][8 * sb + 4], s[kt][8 * sb + 5], s[kt][8 * sb + 6], s[kt][8 * sb + 7]);
; #pragma unroll
;         for (int t = 0; t < 4; ++t) {
;           const bf16x8 vf = *(const bf16x8*)(Vs + (32 * t + l31) * 72 + 32 * kt + 16 * sb + hh * 8);
;           o[t] = MFMA32(vf, pf, o[t]);
;         }
;       }
.LBB0_245:
	v_add_u32_e32 v161, v149, v150
	v_mul_f32_e32 v9, 0xbe38aa3b, v2
	v_fmamk_f32 v0, v96, 0x3e38aa3b, v9
	v_exp_f32_e32 v96, v0
	v_fmamk_f32 v3, v97, 0x3e38aa3b, v9
	v_exp_f32_e32 v97, v3
	v_fmamk_f32 v3, v98, 0x3e38aa3b, v9
	v_exp_f32_e32 v98, v3
	v_fmamk_f32 v3, v99, 0x3e38aa3b, v9
	v_exp_f32_e32 v99, v3
	v_fmamk_f32 v3, v100, 0x3e38aa3b, v9
	v_add_f32_e32 v0, 0, v96
	v_exp_f32_e32 v100, v3
	v_fmamk_f32 v3, v101, 0x3e38aa3b, v9
	v_add_f32_e32 v0, v97, v0
	v_exp_f32_e32 v101, v3
	v_fmamk_f32 v3, v102, 0x3e38aa3b, v9
	v_add_f32_e32 v0, v98, v0
	v_exp_f32_e32 v102, v3
	v_fmamk_f32 v3, v103, 0x3e38aa3b, v9
	v_add_f32_e32 v0, v99, v0
	v_exp_f32_e32 v103, v3
	s_nop 0
	v_cvt_pk_bf16_f32 v242, v96, v97
	v_cvt_pk_bf16_f32 v243, v98, v99
	v_cvt_pk_bf16_f32 v244, v100, v101
	v_cvt_pk_bf16_f32 v245, v102, v103
	s_nop 1
	ds_read_b128 v[96:99], v161 offset:9216
	ds_read_b128 v[162:165], v161 offset:13824
	ds_read_b128 v[166:169], v161 offset:18432
	ds_read_b128 v[170:173], v161 offset:23040
	ds_read_b128 v[174:177], v161 offset:9248
	ds_read_b128 v[178:181], v161 offset:13856
	s_waitcnt lgkmcnt(5)
	v_mfma_f32_32x32x16_bf16 v[64:79], v[96:99], v[242:245], v[64:79]
	ds_read_b128 v[96:99], v161 offset:18464
	v_fmamk_f32 v3, v104, 0x3e38aa3b, v9
	v_add_f32_e32 v0, v100, v0
	v_exp_f32_e32 v104, v3
	v_fmamk_f32 v3, v105, 0x3e38aa3b, v9
	v_add_f32_e32 v0, v101, v0
	v_exp_f32_e32 v105, v3
	s_waitcnt lgkmcnt(5)
	v_mfma_f32_32x32x16_bf16 v[48:63], v[162:165], v[242:245], v[48:63]
	ds_read_b128 v[162:165], v161 offset:23072
	v_fmamk_f32 v3, v106, 0x3e38aa3b, v9
	v_add_f32_e32 v0, v102, v0
	v_exp_f32_e32 v106, v3
	v_fmamk_f32 v3, v107, 0x3e38aa3b, v9
	v_add_f32_e32 v0, v103, v0
	v_exp_f32_e32 v107, v3
	s_waitcnt lgkmcnt(5)
	v_mfma_f32_32x32x16_bf16 v[32:47], v[166:169], v[242:245], v[32:47]
	ds_read_b128 v[166:169], v161 offset:9280
	v_fmamk_f32 v3, v108, 0x3e38aa3b, v9
	v_add_f32_e32 v0, v104, v0
	v_exp_f32_e32 v108, v3
	v_fmamk_f32 v3, v109, 0x3e38aa3b, v9
	v_add_f32_e32 v0, v105, v0
	v_exp_f32_e32 v109, v3
	s_waitcnt lgkmcnt(5)
	v_mfma_f32_32x32x16_bf16 v[16:31], v[170:173], v[242:245], v[16:31]
	ds_read_b128 v[170:173], v161 offset:13888
	v_fmamk_f32 v3, v110, 0x3e38aa3b, v9
	v_add_f32_e32 v0, v106, v0
	v_exp_f32_e32 v110, v3
	v_fmamk_f32 v3, v111, 0x3e38aa3b, v9
	v_add_f32_e32 v0, v107, v0
	v_exp_f32_e32 v111, v3
	s_nop 0
	v_cvt_pk_bf16_f32 v242, v104, v105
	v_cvt_pk_bf16_f32 v243, v106, v107
	v_cvt_pk_bf16_f32 v244, v108, v109
	v_cvt_pk_bf16_f32 v245, v110, v111
	s_nop 1
	s_waitcnt lgkmcnt(5)
	v_mfma_f32_32x32x16_bf16 v[64:79], v[174:177], v[242:245], v[64:79]
	ds_read_b128 v[174:177], v161 offset:18496
	v_fmamk_f32 v3, v80, 0x3e38aa3b, v9
	v_add_f32_e32 v0, v108, v0
	v_exp_f32_e32 v10, v3
	v_fmamk_f32 v3, v81, 0x3e38aa3b, v9
	v_add_f32_e32 v0, v109, v0
	v_exp_f32_e32 v11, v3
	s_waitcnt lgkmcnt(5)
	v_mfma_f32_32x32x16_bf16 v[48:63], v[178:181], v[242:245], v[48:63]
	ds_read_b128 v[178:181], v161 offset:23104
	v_fmamk_f32 v3, v82, 0x3e38aa3b, v9
	v_add_f32_e32 v0, v110, v0
	v_exp_f32_e32 v12, v3
	v_fmamk_f32 v3, v83, 0x3e38aa3b, v9
	v_add_f32_e32 v0, v111, v0
	v_exp_f32_e32 v13, v3
	s_waitcnt lgkmcnt(5)
	v_mfma_f32_32x32x16_bf16 v[32:47], v[96:99], v[242:245], v[32:47]
	ds_read_b128 v[96:99], v161 offset:9312
	v_fmamk_f32 v3, v84, 0x3e38aa3b, v9
	v_add_f32_e32 v0, v10, v0
	v_exp_f32_e32 v14, v3
	v_fmamk_f32 v3, v85, 0x3e38aa3b, v9
	v_add_f32_e32 v0, v11, v0
	v_exp_f32_e32 v15, v3
	s_waitcnt lgkmcnt(5)
	v_mfma_f32_32x32x16_bf16 v[16:31], v[162:165], v[242:245], v[16:31]
	ds_read_b128 v[162:165], v161 offset:13920
	v_fmamk_f32 v3, v86, 0x3e38aa3b, v9
	v_add_f32_e32 v0, v12, v0
	v_exp_f32_e32 v80, v3
	v_fmamk_f32 v3, v87, 0x3e38aa3b, v9
	v_add_f32_e32 v0, v13, v0
	v_exp_f32_e32 v81, v3
	s_nop 0
	v_cvt_pk_bf16_f32 v242, v10, v11
	v_cvt_pk_bf16_f32 v243, v12, v13
	v_cvt_pk_bf16_f32 v244, v14, v15
	v_cvt_pk_bf16_f32 v245, v80, v81
	s_nop 1
	s_waitcnt lgkmcnt(5)
	v_mfma_f32_32x32x16_bf16 v[64:79], v[166:169], v[242:245], v[64:79]
	ds_read_b128 v[166:169], v161 offset:18528
	v_add_f32_e32 v0, v14, v0
	v_add_f32_e32 v0, v15, v0
	v_add_f32_e32 v0, v80, v0
	v_add_f32_e32 v3, v81, v0
	v_fmamk_f32 v0, v88, 0x3e38aa3b, v9
	v_exp_f32_e32 v0, v0
	v_mov_b32_e32 v160, v2
	v_add_f32_e32 v4, v0, v3
	s_waitcnt lgkmcnt(5)
	v_mfma_f32_32x32x16_bf16 v[48:63], v[170:173], v[242:245], v[48:63]
	ds_read_b128 v[170:173], v161 offset:23136
	v_fmamk_f32 v3, v89, 0x3e38aa3b, v9
	v_exp_f32_e32 v3, v3
	s_nop 0
	v_add_f32_e32 v5, v3, v4
	v_fmamk_f32 v4, v90, 0x3e38aa3b, v9
	v_exp_f32_e32 v4, v4
	s_nop 0
	v_add_f32_e32 v6, v4, v5
	s_waitcnt lgkmcnt(5)
	v_mfma_f32_32x32x16_bf16 v[32:47], v[174:177], v[242:245], v[32:47]
	v_fmamk_f32 v5, v91, 0x3e38aa3b, v9
	v_exp_f32_e32 v5, v5
	s_nop 0
	v_add_f32_e32 v7, v5, v6
	v_fmamk_f32 v6, v92, 0x3e38aa3b, v9
	v_exp_f32_e32 v6, v6
	s_nop 0
	v_add_f32_e32 v8, v6, v7
	s_waitcnt lgkmcnt(4)
	v_mfma_f32_32x32x16_bf16 v[16:31], v[178:181], v[242:245], v[16:31]
	v_fmamk_f32 v7, v93, 0x3e38aa3b, v9
	v_exp_f32_e32 v7, v7
	s_nop 0
	v_add_f32_e32 v82, v7, v8
	v_fmamk_f32 v8, v94, 0x3e38aa3b, v9
	v_exp_f32_e32 v8, v8
	v_fmac_f32_e32 v9, 0x3e38aa3b, v95
	v_exp_f32_e32 v9, v9
	s_nop 0
	v_cvt_pk_bf16_f32 v242, v0, v3
	v_cvt_pk_bf16_f32 v243, v4, v5
	v_cvt_pk_bf16_f32 v244, v6, v7
	v_cvt_pk_bf16_f32 v245, v8, v9
	s_nop 1
	s_waitcnt lgkmcnt(3)
	v_mfma_f32_32x32x16_bf16 v[64:79], v[96:99], v[242:245], v[64:79]
	v_add_f32_e32 v82, v8, v82
	s_waitcnt lgkmcnt(2)
	v_mfma_f32_32x32x16_bf16 v[48:63], v[162:165], v[242:245], v[48:63]
	v_add_f32_e32 v82, v9, v82
	s_waitcnt lgkmcnt(1)
	v_mfma_f32_32x32x16_bf16 v[32:47], v[166:169], v[242:245], v[32:47]
	v_add_f32_e32 v148, v82, v148
	s_waitcnt lgkmcnt(0)
	v_mfma_f32_32x32x16_bf16 v[16:31], v[170:173], v[242:245], v[16:31]

; #define MFMA32(a, b, c) __builtin_amdgcn_mfma_f32_32x32x16_bf16((a), (b), (c), 0, 0, 0)
; template <int DQK, int MODE>
; DI void attn_core(const u16* __restrict__ Qg, int ldq, const u16* __restrict__ Kg, int ldk, const u16* __restrict__ Vtg,
;                   const u64* __restrict__ maskg, int q0, float scale, char* smem, int* sflags, f32x16 (&o)[4], float& l_run) {
;     ...
;       for (int kt = 0; kt < 2; ++kt)
; #pragma unroll
;         for (int i = 0; i < 16; ++i) {
;           float pv = __builtin_amdgcn_exp2f(__builtin_fmaf(s[kt][i], sc, msc));
;           if (MODE == 1) pv = (s[kt][i] > -1e29f) ? pv : 0.f;
;           s[kt][i] = pv;
;           ls += pv;
;         }
;     ...
; #pragma unroll
;     for (int kt = 0; kt < 2; ++kt)
; #pragma unroll
;       for (int sb = 0; sb < 2; ++sb) {
;         const bf16x8 pf = pack8(s[kt][8 * sb + 0], s[kt][8 * sb + 1], s[kt][8 * sb + 2], s[kt][8 * sb + 3],
;                                 s[kt][8 * sb + 4], s[kt][8 * sb + 5], s[kt][8 * sb + 6], s[kt][8 * sb + 7]);
; #pragma unroll
;         for (int t = 0; t < 4; ++t) {
;           const bf16x8 vf = *(const bf16x8*)(Vs + (32 * t + l31) * 72 + 32 * kt + 16 * sb + hh * 8);
;           o[t] = MFMA32(vf, pf, o[t]);
;         }
;       }
.LBB0_254:
	v_mul_f32_e32 v0, 0xbe38aa3b, v5
	v_fmamk_f32 v5, v96, 0x3e38aa3b, v0
	v_exp_f32_e32 v96, v5
	v_fmamk_f32 v6, v97, 0x3e38aa3b, v0
	v_exp_f32_e32 v97, v6
	v_fmamk_f32 v6, v98, 0x3e38aa3b, v0
	v_exp_f32_e32 v98, v6
	v_fmamk_f32 v6, v99, 0x3e38aa3b, v0
	v_exp_f32_e32 v99, v6
	v_fmamk_f32 v6, v100, 0x3e38aa3b, v0
	v_add_f32_e32 v5, 0, v96
	v_exp_f32_e32 v100, v6
	v_fmamk_f32 v6, v101, 0x3e38aa3b, v0
	v_add_f32_e32 v5, v97, v5
	v_exp_f32_e32 v101, v6
	v_fmamk_f32 v6, v102, 0x3e38aa3b, v0
	v_add_f32_e32 v5, v98, v5
	v_exp_f32_e32 v102, v6
	v_fmamk_f32 v6, v103, 0x3e38aa3b, v0
	v_add_f32_e32 v5, v99, v5
	v_exp_f32_e32 v103, v6
	v_fmamk_f32 v6, v104, 0x3e38aa3b, v0
	v_add_f32_e32 v5, v100, v5
	v_exp_f32_e32 v104, v6
	v_fmamk_f32 v6, v105, 0x3e38aa3b, v0
	v_add_f32_e32 v5, v101, v5
	v_exp_f32_e32 v105, v6
	v_fmamk_f32 v6, v106, 0x3e38aa3b, v0
	v_add_f32_e32 v5, v102, v5
	v_exp_f32_e32 v106, v6
	v_fmamk_f32 v6, v107, 0x3e38aa3b, v0
	v_add_f32_e32 v5, v103, v5
	v_exp_f32_e32 v107, v6
	v_fmamk_f32 v6, v108, 0x3e38aa3b, v0
	v_add_f32_e32 v5, v104, v5
	v_exp_f32_e32 v108, v6
	v_fmamk_f32 v6, v109, 0x3e38aa3b, v0
	v_add_f32_e32 v5, v105, v5
	v_exp_f32_e32 v109, v6
	v_fmamk_f32 v6, v110, 0x3e38aa3b, v0
	v_add_f32_e32 v5, v106, v5
	v_exp_f32_e32 v110, v6
	v_fmamk_f32 v6, v111, 0x3e38aa3b, v0
	v_add_f32_e32 v5, v107, v5
	v_exp_f32_e32 v111, v6
	v_fmamk_f32 v6, v80, 0x3e38aa3b, v0
	v_add_f32_e32 v5, v108, v5
	v_exp_f32_e32 v13, v6
	v_fmamk_f32 v6, v81, 0x3e38aa3b, v0
	v_add_f32_e32 v5, v109, v5
	v_exp_f32_e32 v14, v6
	v_fmamk_f32 v6, v82, 0x3e38aa3b, v0
	v_add_f32_e32 v5, v110, v5
	v_exp_f32_e32 v15, v6
	v_fmamk_f32 v6, v83, 0x3e38aa3b, v0
	v_add_f32_e32 v5, v111, v5
	v_exp_f32_e32 v80, v6
	v_fmamk_f32 v6, v84, 0x3e38aa3b, v0
	v_add_f32_e32 v5, v13, v5
	v_exp_f32_e32 v81, v6
	v_fmamk_f32 v6, v85, 0x3e38aa3b, v0
	v_add_f32_e32 v5, v14, v5
	v_exp_f32_e32 v82, v6
	v_fmamk_f32 v6, v86, 0x3e38aa3b, v0
	v_add_f32_e32 v5, v15, v5
	v_exp_f32_e32 v83, v6
	v_fmamk_f32 v6, v87, 0x3e38aa3b, v0
	v_add_f32_e32 v5, v80, v5
	v_exp_f32_e32 v84, v6
	v_add_f32_e32 v5, v81, v5
	v_add_f32_e32 v5, v82, v5
	v_add_f32_e32 v5, v83, v5
	v_add_f32_e32 v6, v84, v5
	v_fmamk_f32 v5, v88, 0x3e38aa3b, v0
	v_exp_f32_e32 v5, v5
	s_nop 0
	v_add_f32_e32 v7, v5, v6
	v_fmamk_f32 v6, v89, 0x3e38aa3b, v0
	v_exp_f32_e32 v6, v6
	s_nop 0
	v_cvt_pk_bf16_f32 v242, v96, v97
	v_cvt_pk_bf16_f32 v243, v98, v99
	v_cvt_pk_bf16_f32 v244, v100, v101
	v_cvt_pk_bf16_f32 v245, v102, v103
	s_nop 1
	s_nop 0
	v_add_f32_e32 v8, v6, v7
	v_fmamk_f32 v7, v90, 0x3e38aa3b, v0
	v_exp_f32_e32 v7, v7
	s_nop 0
	v_add_f32_e32 v9, v7, v8
	v_fmamk_f32 v8, v91, 0x3e38aa3b, v0
	v_exp_f32_e32 v8, v8
	s_nop 0
	v_add_f32_e32 v10, v8, v9
	v_fmamk_f32 v9, v92, 0x3e38aa3b, v0
	v_exp_f32_e32 v9, v9
	s_nop 0
	v_add_f32_e32 v11, v9, v10
	v_fmamk_f32 v10, v93, 0x3e38aa3b, v0
	v_exp_f32_e32 v10, v10
	s_nop 0
	v_add_f32_e32 v12, v10, v11
	v_fmamk_f32 v11, v94, 0x3e38aa3b, v0
	v_exp_f32_e32 v11, v11
	v_fmac_f32_e32 v0, 0x3e38aa3b, v95
	v_add_f32_e32 v85, v11, v12
	v_exp_f32_e32 v12, v0
	s_nop 0
	v_add_f32_e32 v0, v12, v85
	v_add_u32_e32 v85, v149, v150
	v_add_f32_e32 v0, v0, v112
	ds_read_b128 v[86:89], v85 offset:9216
	ds_read_b128 v[94:97], v85 offset:13824
	ds_read_b128 v[98:101], v85 offset:18432
	ds_read_b128 v[112:115], v85 offset:23040
	ds_read_b128 v[116:119], v85 offset:9248
	ds_read_b128 v[120:123], v85 offset:13856
	s_waitcnt lgkmcnt(5)
	v_mfma_f32_32x32x16_bf16 v[64:79], v[86:89], v[242:245], v[64:79]
	ds_read_b128 v[86:89], v85 offset:18464
	s_waitcnt lgkmcnt(5)
	v_mfma_f32_32x32x16_bf16 v[48:63], v[94:97], v[242:245], v[48:63]
	ds_read_b128 v[94:97], v85 offset:23072
	s_waitcnt lgkmcnt(5)
	v_mfma_f32_32x32x16_bf16 v[32:47], v[98:101], v[242:245], v[32:47]
	ds_read_b128 v[98:101], v85 offset:9280
	s_waitcnt lgkmcnt(5)
	v_mfma_f32_32x32x16_bf16 v[16:31], v[112:115], v[242:245], v[16:31]
	ds_read_b128 v[112:115], v85 offset:13888
	s_nop 0
	v_cvt_pk_bf16_f32 v242, v104, v105
	v_cvt_pk_bf16_f32 v243, v106, v107
	v_cvt_pk_bf16_f32 v244, v108, v109
	v_cvt_pk_bf16_f32 v245, v110, v111
	s_nop 1
	s_waitcnt lgkmcnt(5)
	v_mfma_f32_32x32x16_bf16 v[64:79], v[116:119], v[242:245], v[64:79]
	ds_read_b128 v[116:119], v85 offset:18496
	s_waitcnt lgkmcnt(5)
	v_mfma_f32_32x32x16_bf16 v[48:63], v[120:123], v[242:245], v[48:63]
	ds_read_b128 v[120:123], v85 offset:23104
	s_waitcnt lgkmcnt(5)
	v_mfma_f32_32x32x16_bf16 v[32:47], v[86:89], v[242:245], v[32:47]
	ds_read_b128 v[86:89], v85 offset:9312
	s_waitcnt lgkmcnt(5)
	v_mfma_f32_32x32x16_bf16 v[16:31], v[94:97], v[242:245], v[16:31]
	ds_read_b128 v[94:97], v85 offset:13920
	s_nop 0
	v_cvt_pk_bf16_f32 v242, v13, v14
	v_cvt_pk_bf16_f32 v243, v15, v80
	v_cvt_pk_bf16_f32 v244, v81, v82
	v_cvt_pk_bf16_f32 v245, v83, v84
	s_nop 1
	s_waitcnt lgkmcnt(5)
	v_mfma_f32_32x32x16_bf16 v[64:79], v[98:101], v[242:245], v[64:79]
	ds_read_b128 v[98:101], v85 offset:18528
	s_waitcnt lgkmcnt(5)
	v_mfma_f32_32x32x16_bf16 v[48:63], v[112:115], v[242:245], v[48:63]
	ds_read_b128 v[112:115], v85 offset:23136
	s_waitcnt lgkmcnt(5)
	v_mfma_f32_32x32x16_bf16 v[32:47], v[116:119], v[242:245], v[32:47]
	s_waitcnt lgkmcnt(4)
	v_mfma_f32_32x32x16_bf16 v[16:31], v[120:123], v[242:245], v[16:31]
	s_nop 0
	v_cvt_pk_bf16_f32 v242, v5, v6
	v_cvt_pk_bf16_f32 v243, v7, v8
	v_cvt_pk_bf16_f32 v244, v9, v10
	v_cvt_pk_bf16_f32 v245, v11, v12
	s_nop 1
	s_waitcnt lgkmcnt(3)
	v_mfma_f32_32x32x16_bf16 v[64:79], v[86:89], v[242:245], v[64:79]
	s_waitcnt lgkmcnt(2)
	v_mfma_f32_32x32x16_bf16 v[48:63], v[94:97], v[242:245], v[48:63]
	s_waitcnt lgkmcnt(1)
	v_mfma_f32_32x32x16_bf16 v[32:47], v[98:101], v[242:245], v[32:47]
	s_waitcnt lgkmcnt(0)
	v_mfma_f32_32x32x16_bf16 v[16:31], v[112:115], v[242:245], v[16:31]

; #define MFMA32(a, b, c) __builtin_amdgcn_mfma_f32_32x32x16_bf16((a), (b), (c), 0, 0, 0)
; template <int DQK, int MODE>
; DI void attn_core(const u16* __restrict__ Qg, int ldq, const u16* __restrict__ Kg, int ldk, const u16* __restrict__ Vtg,
;                   const u64* __restrict__ maskg, int q0, float scale, char* smem, int* sflags, f32x16 (&o)[4], float& l_run) {
;     ...
;       for (int kt = 0; kt < 2; ++kt)
; #pragma unroll
;         for (int i = 0; i < 16; ++i) {
;           float pv = __builtin_amdgcn_exp2f(__builtin_fmaf(s[kt][i], sc, msc));
;           if (MODE == 1) pv = (s[kt][i] > -1e29f) ? pv : 0.f;
;           s[kt][i] = pv;
;           ls += pv;
;         }
;     ...
; #pragma unroll
;     for (int kt = 0; kt < 2; ++kt)
; #pragma unroll
;       for (int sb = 0; sb < 2; ++sb) {
;         const bf16x8 pf = pack8(s[kt][8 * sb + 0], s[kt][8 * sb + 1], s[kt][8 * sb + 2], s[kt][8 * sb + 3],
;                                 s[kt][8 * sb + 4], s[kt][8 * sb + 5], s[kt][8 * sb + 6], s[kt][8 * sb + 7]);
; #pragma unroll
;         for (int t = 0; t < 4; ++t) {
;           const bf16x8 vf = *(const bf16x8*)(Vs + (32 * t + l31) * 72 + 32 * kt + 16 * sb + hh * 8);
;           o[t] = MFMA32(vf, pf, o[t]);
;         }
;       }
.LBB0_263:
	v_add_u32_e32 v163, v142, v152
	v_mul_f32_e32 v9, 0xbe38aa3b, v2
	v_fmamk_f32 v0, v96, 0x3e38aa3b, v9
	v_exp_f32_e32 v96, v0
	v_fmamk_f32 v3, v97, 0x3e38aa3b, v9
	v_exp_f32_e32 v97, v3
	v_fmamk_f32 v3, v98, 0x3e38aa3b, v9
	v_exp_f32_e32 v98, v3
	v_fmamk_f32 v3, v99, 0x3e38aa3b, v9
	v_exp_f32_e32 v99, v3
	v_fmamk_f32 v3, v100, 0x3e38aa3b, v9
	v_add_f32_e32 v0, 0, v96
	v_exp_f32_e32 v100, v3
	v_fmamk_f32 v3, v101, 0x3e38aa3b, v9
	v_add_f32_e32 v0, v97, v0
	v_exp_f32_e32 v101, v3
	v_fmamk_f32 v3, v102, 0x3e38aa3b, v9
	v_add_f32_e32 v0, v98, v0
	v_exp_f32_e32 v102, v3
	v_fmamk_f32 v3, v103, 0x3e38aa3b, v9
	v_add_f32_e32 v0, v99, v0
	v_exp_f32_e32 v103, v3
	s_nop 0
	v_cvt_pk_bf16_f32 v244, v96, v97
	v_cvt_pk_bf16_f32 v245, v98, v99
	v_cvt_pk_bf16_f32 v246, v100, v101
	v_cvt_pk_bf16_f32 v247, v102, v103
	s_nop 1
	ds_read_b128 v[96:99], v163 offset:9216
	ds_read_b128 v[164:167], v163 offset:13824
	ds_read_b128 v[168:171], v163 offset:18432
	ds_read_b128 v[172:175], v163 offset:23040
	ds_read_b128 v[176:179], v163 offset:9248
	ds_read_b128 v[180:183], v163 offset:13856
	s_waitcnt lgkmcnt(5)
	v_mfma_f32_32x32x16_bf16 v[64:79], v[96:99], v[244:247], v[64:79]
	ds_read_b128 v[96:99], v163 offset:18464
	v_fmamk_f32 v3, v104, 0x3e38aa3b, v9
	v_add_f32_e32 v0, v100, v0
	v_exp_f32_e32 v104, v3
	v_fmamk_f32 v3, v105, 0x3e38aa3b, v9
	v_add_f32_e32 v0, v101, v0
	v_exp_f32_e32 v105, v3
	s_waitcnt lgkmcnt(5)
	v_mfma_f32_32x32x16_bf16 v[48:63], v[164:167], v[244:247], v[48:63]
	ds_read_b128 v[164:167], v163 offset:23072
	v_fmamk_f32 v3, v106, 0x3e38aa3b, v9
	v_add_f32_e32 v0, v102, v0
	v_exp_f32_e32 v106, v3
	v_fmamk_f32 v3, v107, 0x3e38aa3b, v9
	v_add_f32_e32 v0, v103, v0
	v_exp_f32_e32 v107, v3
	s_waitcnt lgkmcnt(5)
	v_mfma_f32_32x32x16_bf16 v[32:47], v[168:171], v[244:247], v[32:47]
	ds_read_b128 v[168:171], v163 offset:9280
	v_fmamk_f32 v3, v108, 0x3e38aa3b, v9
	v_add_f32_e32 v0, v104, v0
	v_exp_f32_e32 v108, v3
	v_fmamk_f32 v3, v109, 0x3e38aa3b, v9
	v_add_f32_e32 v0, v105, v0
	v_exp_f32_e32 v109, v3
	s_waitcnt lgkmcnt(5)
	v_mfma_f32_32x32x16_bf16 v[16:31], v[172:175], v[244:247], v[16:31]
	ds_read_b128 v[172:175], v163 offset:13888
	v_fmamk_f32 v3, v110, 0x3e38aa3b, v9
	v_add_f32_e32 v0, v106, v0
	v_exp_f32_e32 v110, v3
	v_fmamk_f32 v3, v111, 0x3e38aa3b, v9
	v_add_f32_e32 v0, v107, v0
	v_exp_f32_e32 v111, v3
	s_nop 0
	v_cvt_pk_bf16_f32 v244, v104, v105
	v_cvt_pk_bf16_f32 v245, v106, v107
	v_cvt_pk_bf16_f32 v246, v108, v109
	v_cvt_pk_bf16_f32 v247, v110, v111
	s_nop 1
	s_waitcnt lgkmcnt(5)
	v_mfma_f32_32x32x16_bf16 v[64:79], v[176:179], v[244:247], v[64:79]
	ds_read_b128 v[176:179], v163 offset:18496
	v_fmamk_f32 v3, v80, 0x3e38aa3b, v9
	v_add_f32_e32 v0, v108, v0
	v_exp_f32_e32 v10, v3
	v_fmamk_f32 v3, v81, 0x3e38aa3b, v9
	v_add_f32_e32 v0, v109, v0
	v_exp_f32_e32 v11, v3
	s_waitcnt lgkmcnt(5)
	v_mfma_f32_32x32x16_bf16 v[48:63], v[180:183], v[244:247], v[48:63]
	ds_read_b128 v[180:183], v163 offset:23104
	v_fmamk_f32 v3, v82, 0x3e38aa3b, v9
	v_add_f32_e32 v0, v110, v0
	v_exp_f32_e32 v12, v3
	v_fmamk_f32 v3, v83, 0x3e38aa3b, v9
	v_add_f32_e32 v0, v111, v0
	v_exp_f32_e32 v13, v3
	s_waitcnt lgkmcnt(5)
	v_mfma_f32_32x32x16_bf16 v[32:47], v[96:99], v[244:247], v[32:47]
	ds_read_b128 v[96:99], v163 offset:9312
	v_fmamk_f32 v3, v84, 0x3e38aa3b, v9
	v_add_f32_e32 v0, v10, v0
	v_exp_f32_e32 v14, v3
	v_fmamk_f32 v3, v85, 0x3e38aa3b, v9
	v_add_f32_e32 v0, v11, v0
	v_exp_f32_e32 v15, v3
	s_waitcnt lgkmcnt(5)
	v_mfma_f32_32x32x16_bf16 v[16:31], v[164:167], v[244:247], v[16:31]
	ds_read_b128 v[164:167], v163 offset:13920
	v_fmamk_f32 v3, v86, 0x3e38aa3b, v9
	v_add_f32_e32 v0, v12, v0
	v_exp_f32_e32 v80, v3
	v_fmamk_f32 v3, v87, 0x3e38aa3b, v9
	v_add_f32_e32 v0, v13, v0
	v_exp_f32_e32 v81, v3
	s_nop 0
	v_cvt_pk_bf16_f32 v244, v10, v11
	v_cvt_pk_bf16_f32 v245, v12, v13
	v_cvt_pk_bf16_f32 v246, v14, v15
	v_cvt_pk_bf16_f32 v247, v80, v81
	s_nop 1
	s_waitcnt lgkmcnt(5)
	v_mfma_f32_32x32x16_bf16 v[64:79], v[168:171], v[244:247], v[64:79]
	ds_read_b128 v[168:171], v163 offset:18528
	v_add_f32_e32 v0, v14, v0
	v_add_f32_e32 v0, v15, v0
	v_add_f32_e32 v0, v80, v0
	v_add_f32_e32 v3, v81, v0
	v_fmamk_f32 v0, v88, 0x3e38aa3b, v9
	v_exp_f32_e32 v0, v0
	v_mov_b32_e32 v162, v2
	v_add_f32_e32 v4, v0, v3
	s_waitcnt lgkmcnt(5)
	v_mfma_f32_32x32x16_bf16 v[48:63], v[172:175], v[244:247], v[48:63]
	ds_read_b128 v[172:175], v163 offset:23136
	v_fmamk_f32 v3, v89, 0x3e38aa3b, v9
	v_exp_f32_e32 v3, v3
	s_nop 0
	v_add_f32_e32 v5, v3, v4
	v_fmamk_f32 v4, v90, 0x3e38aa3b, v9
	v_exp_f32_e32 v4, v4
	s_nop 0
	v_add_f32_e32 v6, v4, v5
	s_waitcnt lgkmcnt(5)
	v_mfma_f32_32x32x16_bf16 v[32:47], v[176:179], v[244:247], v[32:47]
	v_fmamk_f32 v5, v91, 0x3e38aa3b, v9
	v_exp_f32_e32 v5, v5
	s_nop 0
	v_add_f32_e32 v7, v5, v6
	v_fmamk_f32 v6, v92, 0x3e38aa3b, v9
	v_exp_f32_e32 v6, v6
	s_nop 0
	v_add_f32_e32 v8, v6, v7
	s_waitcnt lgkmcnt(4)
	v_mfma_f32_32x32x16_bf16 v[16:31], v[180:183], v[244:247], v[16:31]
	v_fmamk_f32 v7, v93, 0x3e38aa3b, v9
	v_exp_f32_e32 v7, v7
	s_nop 0
	v_add_f32_e32 v82, v7, v8
	v_fmamk_f32 v8, v94, 0x3e38aa3b, v9
	v_exp_f32_e32 v8, v8
	v_fmac_f32_e32 v9, 0x3e38aa3b, v95
	v_exp_f32_e32 v9, v9
	s_nop 0
	v_cvt_pk_bf16_f32 v244, v0, v3
	v_cvt_pk_bf16_f32 v245, v4, v5
	v_cvt_pk_bf16_f32 v246, v6, v7
	v_cvt_pk_bf16_f32 v247, v8, v9
	s_nop 1
	s_waitcnt lgkmcnt(3)
	v_mfma_f32_32x32x16_bf16 v[64:79], v[96:99], v[244:247], v[64:79]
	v_add_f32_e32 v82, v8, v82
	s_waitcnt lgkmcnt(2)
	v_mfma_f32_32x32x16_bf16 v[48:63], v[164:167], v[244:247], v[48:63]
	v_add_f32_e32 v82, v9, v82
	s_waitcnt lgkmcnt(1)
	v_mfma_f32_32x32x16_bf16 v[32:47], v[168:171], v[244:247], v[32:47]
	v_add_f32_e32 v143, v82, v143
	s_waitcnt lgkmcnt(0)
	v_mfma_f32_32x32x16_bf16 v[16:31], v[172:175], v[244:247], v[16:31]
